# EpiResid fast path (ao/ho/dn): h and P outputs lane-transposed via ds_bpermute so adjacent lanes store the same row's pieces (16 line requests per store instead of 64)
# baseline (speedup 1.0000x reference)
; __device__ __forceinline__ unsigned cvtpk(float lo, float hi) { f32x2 v = {lo, hi}; bf16x2_t b = __builtin_convertvector(v, bf16x2_t); return __builtin_bit_cast(unsigned, b); }
;     __device__ __forceinline__ void operator()(const f32x4 (&acc)[2][2][4][2], const pg8::Unit& u, int wr, int wc, int fr, int fq) const {
;     ...
;                 const int grow = row_base + u.pm * 256 + ai * 128 + wr * 64 + m * 16 + fr;
;                 const bool ok = grow < MREAL;
;                 float ss = 0.f;
;                 if (ok) {
;                     const float* src; float* dst;
;                     if (grow < ROWS_P) { src = srcA + (size_t)grow * DM; dst = dstMain + (size_t)grow * DM; }
;                     else if (grow < ROWS_MAIN) { src = srcB + (size_t)(grow - ROWS_P) * DM; dst = dstMain + (size_t)grow * DM; }
;                     else { const int mr = grow - ROWS_MAIN; src = srcM + (size_t)(mr & meta_mask) * DM; dst = dstM + (size_t)mr * DM; }
; #pragma unroll
;                     for (int bj = 0; bj < 2; ++bj) {
;                         const int col0 = u.pn * 256 + bj * 128 + wc * 32 + 8 * fq;
;                         const f32x4 h0 = *(const f32x4*)(src + col0) + acc[ai][bj][m][0];
;                         const f32x4 h1 = *(const f32x4*)(src + col0 + 4) + acc[ai][bj][m][1];
;                         *(f32x4*)(dst + col0) = h0; *(f32x4*)(dst + col0 + 4) = h1;
;                         if (P) { u32x4 w; w.x = cvtpk(h0[0], h0[1]); w.y = cvtpk(h0[2], h0[3]); w.z = cvtpk(h1[0], h1[1]); w.w = cvtpk(h1[2], h1[3]);
;                             *(u32x4*)(P + (size_t)grow * DM + col0) = w; }
;                         ss += (h0[0] * h0[0] + h0[1] * h0[1]) + (h0[2] * h0[2] + h0[3] * h0[3]) + (h1[0] * h1[0] + h1[1] * h1[1]) + (h1[2] * h1[2] + h1[3] * h1[3]);
;                     }
;                 }
;                 ss += __shfl_xor(ss, 16); ss += __shfl_xor(ss, 32);
;                 if (ok && fq == 0 && rowss_next) atomicAdd(rowss_next + grow, (u64)(ss * SS_SCALE));
.LBB0_798:
	s_lshl_b32 vcc_lo, s42, 8
	s_cmp_lt_u32 vcc_lo, 0x18000
	s_cbranch_scc0 .Lepi_old_ao
	s_cmp_lg_u64 s[28:29], 0
	s_cbranch_scc0 .Lepi_old_ao
	s_cmp_lg_u64 s[30:31], 0
	s_cbranch_scc0 .Lepi_old_ao
	s_lshl_b32 vcc_hi, s8, 10
	s_lshl_b32 s8, vcc_lo, 3
	s_add_u32 s8, s16, s8
	s_addc_u32 s9, s17, 0
	s_lshl_b32 s6, vcc_lo, 12
	s_add_u32 vcc_hi, vcc_hi, s6
	s_add_u32 s44, s12, vcc_hi
	s_addc_u32 s45, s13, 0
	s_lshr_b32 s6, vcc_hi, 1
	s_add_u32 s6, s10, s6
	s_addc_u32 s7, s11, 0
	s_cmp_lt_u32 vcc_lo, 0x8000
	s_cselect_b32 s42, s24, s22
	s_cselect_b32 s43, s25, s23
	s_cselect_b32 vcc_lo, 0, 0x8000000
	s_sub_u32 vcc_hi, vcc_hi, vcc_lo
	s_add_u32 s42, s42, vcc_hi
	s_addc_u32 s43, s43, 0
	v_lshlrev_b32_e32 v150, 12, v164
	v_lshl_add_u32 v150, v166, 2, v150
	v_lshrrev_b32_e32 v151, 1, v150
	v_lshlrev_b32_e32 v162, 3, v164
	v_mbcnt_lo_u32_b32 v235, -1, 0
	v_mbcnt_hi_u32_b32 v235, -1, v235
	v_and_b32_e32 v232, 3, v235
	v_lshlrev_b32_e32 v232, 6, v232
	v_and_b32_e32 v236, 60, v235
	v_or_b32_e32 v232, v232, v236
	v_lshrrev_b32_e32 v236, 2, v235
	v_and_b32_e32 v237, 15, v235
	v_sub_u32_e32 v236, v236, v237
	v_lshl_add_u32 v233, v236, 12, v150
	v_and_b32_e32 v236, 3, v235
	v_lshrrev_b32_e32 v237, 4, v235
	v_sub_u32_e32 v236, v236, v237
	v_lshl_add_u32 v233, v236, 5, v233
	v_lshrrev_b32_e32 v234, 1, v233
	global_load_dwordx4 v[168:171], v150, s[42:43]
	global_load_dwordx4 v[172:175], v150, s[42:43] offset:16
	global_load_dwordx4 v[176:179], v150, s[42:43] offset:512
	global_load_dwordx4 v[180:183], v150, s[42:43] offset:528
	s_add_u32 s42, s42, 0x10000
	s_addc_u32 s43, s43, 0
	global_load_dwordx4 v[184:187], v150, s[42:43]
	global_load_dwordx4 v[188:191], v150, s[42:43] offset:16
	global_load_dwordx4 v[192:195], v150, s[42:43] offset:512
	global_load_dwordx4 v[196:199], v150, s[42:43] offset:528
	s_add_u32 s42, s42, 0x10000
	s_addc_u32 s43, s43, 0
	global_load_dwordx4 v[216:219], v150, s[42:43]
	global_load_dwordx4 v[220:223], v150, s[42:43] offset:16
	global_load_dwordx4 v[224:227], v150, s[42:43] offset:512
	global_load_dwordx4 v[228:231], v150, s[42:43] offset:528
	s_add_u32 s42, s42, 0x10000
	s_addc_u32 s43, s43, 0
	global_load_dwordx4 v[142:145], v150, s[42:43]
	global_load_dwordx4 v[146:149], v150, s[42:43] offset:16
	global_load_dwordx4 v[158:161], v150, s[42:43] offset:512
	global_load_dwordx4 v[204:207], v150, s[42:43] offset:528
	s_add_u32 s42, s42, 0x50000
	s_addc_u32 s43, s43, 0
	s_waitcnt vmcnt(12)
	v_pk_add_f32 v[126:127], v[126:127], v[168:169]
	v_pk_add_f32 v[128:129], v[128:129], v[170:171]
	v_pk_add_f32 v[122:123], v[122:123], v[172:173]
	v_pk_add_f32 v[124:125], v[124:125], v[174:175]
	v_pk_add_f32 v[118:119], v[118:119], v[176:177]
	v_pk_add_f32 v[120:121], v[120:121], v[178:179]
	v_pk_add_f32 v[114:115], v[114:115], v[180:181]
	v_pk_add_f32 v[116:117], v[116:117], v[182:183]
	v_cvt_pk_bf16_f32 v168, v126, v127
	v_cvt_pk_bf16_f32 v169, v128, v129
	v_cvt_pk_bf16_f32 v170, v122, v123
	v_cvt_pk_bf16_f32 v171, v124, v125
	v_cvt_pk_bf16_f32 v172, v118, v119
	v_cvt_pk_bf16_f32 v173, v120, v121
	v_cvt_pk_bf16_f32 v174, v114, v115
	v_cvt_pk_bf16_f32 v175, v116, v117
	v_mul_f32_e32 v163, v126, v126
	v_mul_f32_e32 v200, v127, v127
	v_fmac_f32_e32 v163, v128, v128
	v_fmac_f32_e32 v200, v129, v129
	v_fmac_f32_e32 v163, v122, v122
	v_fmac_f32_e32 v200, v123, v123
	v_fmac_f32_e32 v163, v124, v124
	v_fmac_f32_e32 v200, v125, v125
	v_fmac_f32_e32 v163, v118, v118
	v_fmac_f32_e32 v200, v119, v119
	v_fmac_f32_e32 v163, v120, v120
	v_fmac_f32_e32 v200, v121, v121
	v_fmac_f32_e32 v163, v114, v114
	v_fmac_f32_e32 v200, v115, v115
	v_fmac_f32_e32 v163, v116, v116
	v_fmac_f32_e32 v200, v117, v117
	ds_bpermute_b32 v126, v232, v126
	ds_bpermute_b32 v127, v232, v127
	ds_bpermute_b32 v128, v232, v128
	ds_bpermute_b32 v129, v232, v129
	ds_bpermute_b32 v122, v232, v122
	ds_bpermute_b32 v123, v232, v123
	ds_bpermute_b32 v124, v232, v124
	ds_bpermute_b32 v125, v232, v125
	ds_bpermute_b32 v118, v232, v118
	ds_bpermute_b32 v119, v232, v119
	ds_bpermute_b32 v120, v232, v120
	ds_bpermute_b32 v121, v232, v121
	ds_bpermute_b32 v114, v232, v114
	ds_bpermute_b32 v115, v232, v115
	ds_bpermute_b32 v116, v232, v116
	ds_bpermute_b32 v117, v232, v117
	ds_bpermute_b32 v168, v232, v168
	ds_bpermute_b32 v169, v232, v169
	ds_bpermute_b32 v170, v232, v170
	ds_bpermute_b32 v171, v232, v171
	ds_bpermute_b32 v172, v232, v172
	ds_bpermute_b32 v173, v232, v173
	ds_bpermute_b32 v174, v232, v174
	ds_bpermute_b32 v175, v232, v175
	s_waitcnt lgkmcnt(0)
	global_store_dwordx4 v233, v[126:129], s[44:45]
	global_store_dwordx4 v233, v[122:125], s[44:45] offset:16
	global_store_dwordx4 v233, v[118:121], s[44:45] offset:512
	global_store_dwordx4 v233, v[114:117], s[44:45] offset:528
	global_store_dwordx4 v234, v[168:171], s[6:7]
	global_store_dwordx4 v234, v[172:175], s[6:7] offset:256
	v_add_f32_e32 v114, v163, v200
	s_add_u32 s44, s44, 0x10000
	s_addc_u32 s45, s45, 0
	s_add_u32 s6, s6, 0x8000
	s_addc_u32 s7, s7, 0
	global_load_dwordx4 v[168:171], v150, s[42:43]
	global_load_dwordx4 v[172:175], v150, s[42:43] offset:16
	global_load_dwordx4 v[176:179], v150, s[42:43] offset:512
	global_load_dwordx4 v[180:183], v150, s[42:43] offset:528
	s_add_u32 s42, s42, 0x10000
	s_addc_u32 s43, s43, 0
	s_waitcnt vmcnt(18)
; __device__ __forceinline__ unsigned cvtpk(float lo, float hi) { f32x2 v = {lo, hi}; bf16x2_t b = __builtin_convertvector(v, bf16x2_t); return __builtin_bit_cast(unsigned, b); }
;     __device__ __forceinline__ void operator()(const f32x4 (&acc)[2][2][4][2], const pg8::Unit& u, int wr, int wc, int fr, int fq) const {
;     ...
;                     for (int bj = 0; bj < 2; ++bj) {
;                         const int col0 = u.pn * 256 + bj * 128 + wc * 32 + 8 * fq;
;                         const f32x4 h0 = *(const f32x4*)(src + col0) + acc[ai][bj][m][0];
;                         const f32x4 h1 = *(const f32x4*)(src + col0 + 4) + acc[ai][bj][m][1];
;                         *(f32x4*)(dst + col0) = h0; *(f32x4*)(dst + col0 + 4) = h1;
;                         if (P) { u32x4 w; w.x = cvtpk(h0[0], h0[1]); w.y = cvtpk(h0[2], h0[3]); w.z = cvtpk(h1[0], h1[1]); w.w = cvtpk(h1[2], h1[3]);
;                             *(u32x4*)(P + (size_t)grow * DM + col0) = w; }
;                         ss += (h0[0] * h0[0] + h0[1] * h0[1]) + (h0[2] * h0[2] + h0[3] * h0[3]) + (h1[0] * h1[0] + h1[1] * h1[1]) + (h1[2] * h1[2] + h1[3] * h1[3]);
;                     }
	v_pk_add_f32 v[110:111], v[110:111], v[184:185]
	v_pk_add_f32 v[112:113], v[112:113], v[186:187]
	v_pk_add_f32 v[106:107], v[106:107], v[188:189]
	v_pk_add_f32 v[108:109], v[108:109], v[190:191]
	v_pk_add_f32 v[102:103], v[102:103], v[192:193]
	v_pk_add_f32 v[104:105], v[104:105], v[194:195]
	v_pk_add_f32 v[98:99], v[98:99], v[196:197]
	v_pk_add_f32 v[100:101], v[100:101], v[198:199]
	v_cvt_pk_bf16_f32 v184, v110, v111
	v_cvt_pk_bf16_f32 v185, v112, v113
	v_cvt_pk_bf16_f32 v186, v106, v107
	v_cvt_pk_bf16_f32 v187, v108, v109
	v_cvt_pk_bf16_f32 v188, v102, v103
	v_cvt_pk_bf16_f32 v189, v104, v105
	v_cvt_pk_bf16_f32 v190, v98, v99
	v_cvt_pk_bf16_f32 v191, v100, v101
	v_mul_f32_e32 v163, v110, v110
	v_mul_f32_e32 v200, v111, v111
	v_fmac_f32_e32 v163, v112, v112
	v_fmac_f32_e32 v200, v113, v113
	v_fmac_f32_e32 v163, v106, v106
	v_fmac_f32_e32 v200, v107, v107
	v_fmac_f32_e32 v163, v108, v108
	v_fmac_f32_e32 v200, v109, v109
	v_fmac_f32_e32 v163, v102, v102
	v_fmac_f32_e32 v200, v103, v103
	v_fmac_f32_e32 v163, v104, v104
	v_fmac_f32_e32 v200, v105, v105
	v_fmac_f32_e32 v163, v98, v98
	v_fmac_f32_e32 v200, v99, v99
	v_fmac_f32_e32 v163, v100, v100
	v_fmac_f32_e32 v200, v101, v101
	ds_bpermute_b32 v110, v232, v110
	ds_bpermute_b32 v111, v232, v111
	ds_bpermute_b32 v112, v232, v112
	ds_bpermute_b32 v113, v232, v113
	ds_bpermute_b32 v106, v232, v106
	ds_bpermute_b32 v107, v232, v107
	ds_bpermute_b32 v108, v232, v108
	ds_bpermute_b32 v109, v232, v109
	ds_bpermute_b32 v102, v232, v102
	ds_bpermute_b32 v103, v232, v103
	ds_bpermute_b32 v104, v232, v104
	ds_bpermute_b32 v105, v232, v105
	ds_bpermute_b32 v98, v232, v98
	ds_bpermute_b32 v99, v232, v99
	ds_bpermute_b32 v100, v232, v100
	ds_bpermute_b32 v101, v232, v101
	ds_bpermute_b32 v184, v232, v184
	ds_bpermute_b32 v185, v232, v185
	ds_bpermute_b32 v186, v232, v186
	ds_bpermute_b32 v187, v232, v187
	ds_bpermute_b32 v188, v232, v188
	ds_bpermute_b32 v189, v232, v189
	ds_bpermute_b32 v190, v232, v190
	ds_bpermute_b32 v191, v232, v191
	s_waitcnt lgkmcnt(0)
	global_store_dwordx4 v233, v[110:113], s[44:45]
	global_store_dwordx4 v233, v[106:109], s[44:45] offset:16
	global_store_dwordx4 v233, v[102:105], s[44:45] offset:512
	global_store_dwordx4 v233, v[98:101], s[44:45] offset:528
	global_store_dwordx4 v234, v[184:187], s[6:7]
	global_store_dwordx4 v234, v[188:191], s[6:7] offset:256
	v_add_f32_e32 v98, v163, v200
	s_add_u32 s44, s44, 0x10000
	s_addc_u32 s45, s45, 0
	s_add_u32 s6, s6, 0x8000
	s_addc_u32 s7, s7, 0
	global_load_dwordx4 v[184:187], v150, s[42:43]
	global_load_dwordx4 v[188:191], v150, s[42:43] offset:16
	global_load_dwordx4 v[192:195], v150, s[42:43] offset:512
	global_load_dwordx4 v[196:199], v150, s[42:43] offset:528
	s_add_u32 s42, s42, 0x10000
	s_addc_u32 s43, s43, 0
	s_waitcnt vmcnt(24)
	v_pk_add_f32 v[94:95], v[94:95], v[216:217]
	v_pk_add_f32 v[96:97], v[96:97], v[218:219]
	v_pk_add_f32 v[90:91], v[90:91], v[220:221]
	v_pk_add_f32 v[92:93], v[92:93], v[222:223]
	v_pk_add_f32 v[86:87], v[86:87], v[224:225]
	v_pk_add_f32 v[88:89], v[88:89], v[226:227]
	v_pk_add_f32 v[82:83], v[82:83], v[228:229]
	v_pk_add_f32 v[84:85], v[84:85], v[230:231]
	v_cvt_pk_bf16_f32 v216, v94, v95
	v_cvt_pk_bf16_f32 v217, v96, v97
	v_cvt_pk_bf16_f32 v218, v90, v91
	v_cvt_pk_bf16_f32 v219, v92, v93
	v_cvt_pk_bf16_f32 v220, v86, v87
	v_cvt_pk_bf16_f32 v221, v88, v89
	v_cvt_pk_bf16_f32 v222, v82, v83
	v_cvt_pk_bf16_f32 v223, v84, v85
	v_mul_f32_e32 v163, v94, v94
	v_mul_f32_e32 v200, v95, v95
	v_fmac_f32_e32 v163, v96, v96
	v_fmac_f32_e32 v200, v97, v97
	v_fmac_f32_e32 v163, v90, v90
	v_fmac_f32_e32 v200, v91, v91
	v_fmac_f32_e32 v163, v92, v92
	v_fmac_f32_e32 v200, v93, v93
	v_fmac_f32_e32 v163, v86, v86
	v_fmac_f32_e32 v200, v87, v87
	v_fmac_f32_e32 v163, v88, v88
	v_fmac_f32_e32 v200, v89, v89
	v_fmac_f32_e32 v163, v82, v82
	v_fmac_f32_e32 v200, v83, v83
	v_fmac_f32_e32 v163, v84, v84
	v_fmac_f32_e32 v200, v85, v85
	ds_bpermute_b32 v94, v232, v94
	ds_bpermute_b32 v95, v232, v95
	ds_bpermute_b32 v96, v232, v96
	ds_bpermute_b32 v97, v232, v97
	ds_bpermute_b32 v90, v232, v90
	ds_bpermute_b32 v91, v232, v91
	ds_bpermute_b32 v92, v232, v92
	ds_bpermute_b32 v93, v232, v93
	ds_bpermute_b32 v86, v232, v86
	ds_bpermute_b32 v87, v232, v87
	ds_bpermute_b32 v88, v232, v88
	ds_bpermute_b32 v89, v232, v89
	ds_bpermute_b32 v82, v232, v82
	ds_bpermute_b32 v83, v232, v83
	ds_bpermute_b32 v84, v232, v84
	ds_bpermute_b32 v85, v232, v85
	ds_bpermute_b32 v216, v232, v216
	ds_bpermute_b32 v217, v232, v217
	ds_bpermute_b32 v218, v232, v218
	ds_bpermute_b32 v219, v232, v219
	ds_bpermute_b32 v220, v232, v220
	ds_bpermute_b32 v221, v232, v221
	ds_bpermute_b32 v222, v232, v222
	ds_bpermute_b32 v223, v232, v223
	s_waitcnt lgkmcnt(0)
	global_store_dwordx4 v233, v[94:97], s[44:45]
	global_store_dwordx4 v233, v[90:93], s[44:45] offset:16
	global_store_dwordx4 v233, v[86:89], s[44:45] offset:512
	global_store_dwordx4 v233, v[82:85], s[44:45] offset:528
	global_store_dwordx4 v234, v[216:219], s[6:7]
	global_store_dwordx4 v234, v[220:223], s[6:7] offset:256
	v_add_f32_e32 v82, v163, v200
	s_add_u32 s44, s44, 0x10000
	s_addc_u32 s45, s45, 0
	s_add_u32 s6, s6, 0x8000
	s_addc_u32 s7, s7, 0
	global_load_dwordx4 v[216:219], v150, s[42:43]
	global_load_dwordx4 v[220:223], v150, s[42:43] offset:16
	global_load_dwordx4 v[224:227], v150, s[42:43] offset:512
	global_load_dwordx4 v[228:231], v150, s[42:43] offset:528
	s_add_u32 s42, s42, 0x10000
	s_addc_u32 s43, s43, 0
	s_waitcnt vmcnt(30)
; __device__ __forceinline__ unsigned cvtpk(float lo, float hi) { f32x2 v = {lo, hi}; bf16x2_t b = __builtin_convertvector(v, bf16x2_t); return __builtin_bit_cast(unsigned, b); }
;     __device__ __forceinline__ void operator()(const f32x4 (&acc)[2][2][4][2], const pg8::Unit& u, int wr, int wc, int fr, int fq) const {
;     ...
;                     for (int bj = 0; bj < 2; ++bj) {
;                         const int col0 = u.pn * 256 + bj * 128 + wc * 32 + 8 * fq;
;                         const f32x4 h0 = *(const f32x4*)(src + col0) + acc[ai][bj][m][0];
;                         const f32x4 h1 = *(const f32x4*)(src + col0 + 4) + acc[ai][bj][m][1];
;                         *(f32x4*)(dst + col0) = h0; *(f32x4*)(dst + col0 + 4) = h1;
;                         if (P) { u32x4 w; w.x = cvtpk(h0[0], h0[1]); w.y = cvtpk(h0[2], h0[3]); w.z = cvtpk(h1[0], h1[1]); w.w = cvtpk(h1[2], h1[3]);
;                             *(u32x4*)(P + (size_t)grow * DM + col0) = w; }
;                         ss += (h0[0] * h0[0] + h0[1] * h0[1]) + (h0[2] * h0[2] + h0[3] * h0[3]) + (h1[0] * h1[0] + h1[1] * h1[1]) + (h1[2] * h1[2] + h1[3] * h1[3]);
;                     }
	v_pk_add_f32 v[78:79], v[78:79], v[142:143]
	v_pk_add_f32 v[80:81], v[80:81], v[144:145]
	v_pk_add_f32 v[74:75], v[74:75], v[146:147]
	v_pk_add_f32 v[76:77], v[76:77], v[148:149]
	v_pk_add_f32 v[70:71], v[70:71], v[158:159]
	v_pk_add_f32 v[72:73], v[72:73], v[160:161]
	v_pk_add_f32 v[66:67], v[66:67], v[204:205]
	v_pk_add_f32 v[68:69], v[68:69], v[206:207]
	v_cvt_pk_bf16_f32 v142, v78, v79
	v_cvt_pk_bf16_f32 v143, v80, v81
	v_cvt_pk_bf16_f32 v144, v74, v75
	v_cvt_pk_bf16_f32 v145, v76, v77
	v_cvt_pk_bf16_f32 v146, v70, v71
	v_cvt_pk_bf16_f32 v147, v72, v73
	v_cvt_pk_bf16_f32 v148, v66, v67
	v_cvt_pk_bf16_f32 v149, v68, v69
	v_mul_f32_e32 v163, v78, v78
	v_mul_f32_e32 v200, v79, v79
	v_fmac_f32_e32 v163, v80, v80
	v_fmac_f32_e32 v200, v81, v81
	v_fmac_f32_e32 v163, v74, v74
	v_fmac_f32_e32 v200, v75, v75
	v_fmac_f32_e32 v163, v76, v76
	v_fmac_f32_e32 v200, v77, v77
	v_fmac_f32_e32 v163, v70, v70
	v_fmac_f32_e32 v200, v71, v71
	v_fmac_f32_e32 v163, v72, v72
	v_fmac_f32_e32 v200, v73, v73
	v_fmac_f32_e32 v163, v66, v66
	v_fmac_f32_e32 v200, v67, v67
	v_fmac_f32_e32 v163, v68, v68
	v_fmac_f32_e32 v200, v69, v69
	ds_bpermute_b32 v78, v232, v78
	ds_bpermute_b32 v79, v232, v79
	ds_bpermute_b32 v80, v232, v80
	ds_bpermute_b32 v81, v232, v81
	ds_bpermute_b32 v74, v232, v74
	ds_bpermute_b32 v75, v232, v75
	ds_bpermute_b32 v76, v232, v76
	ds_bpermute_b32 v77, v232, v77
	ds_bpermute_b32 v70, v232, v70
	ds_bpermute_b32 v71, v232, v71
	ds_bpermute_b32 v72, v232, v72
	ds_bpermute_b32 v73, v232, v73
	ds_bpermute_b32 v66, v232, v66
	ds_bpermute_b32 v67, v232, v67
	ds_bpermute_b32 v68, v232, v68
	ds_bpermute_b32 v69, v232, v69
	ds_bpermute_b32 v142, v232, v142
	ds_bpermute_b32 v143, v232, v143
	ds_bpermute_b32 v144, v232, v144
	ds_bpermute_b32 v145, v232, v145
	ds_bpermute_b32 v146, v232, v146
	ds_bpermute_b32 v147, v232, v147
	ds_bpermute_b32 v148, v232, v148
	ds_bpermute_b32 v149, v232, v149
	s_waitcnt lgkmcnt(0)
	global_store_dwordx4 v233, v[78:81], s[44:45]
	global_store_dwordx4 v233, v[74:77], s[44:45] offset:16
	global_store_dwordx4 v233, v[70:73], s[44:45] offset:512
	global_store_dwordx4 v233, v[66:69], s[44:45] offset:528
	global_store_dwordx4 v234, v[142:145], s[6:7]
	global_store_dwordx4 v234, v[146:149], s[6:7] offset:256
	v_add_f32_e32 v66, v163, v200
	s_add_u32 s44, s44, 0x50000
	s_addc_u32 s45, s45, 0
	s_add_u32 s6, s6, 0x28000
	s_addc_u32 s7, s7, 0
	global_load_dwordx4 v[142:145], v150, s[42:43]
	global_load_dwordx4 v[146:149], v150, s[42:43] offset:16
	global_load_dwordx4 v[158:161], v150, s[42:43] offset:512
	global_load_dwordx4 v[204:207], v150, s[42:43] offset:528
	s_waitcnt vmcnt(30)
	v_pk_add_f32 v[62:63], v[62:63], v[168:169]
	v_pk_add_f32 v[64:65], v[64:65], v[170:171]
	v_pk_add_f32 v[58:59], v[58:59], v[172:173]
	v_pk_add_f32 v[60:61], v[60:61], v[174:175]
	v_pk_add_f32 v[54:55], v[54:55], v[176:177]
	v_pk_add_f32 v[56:57], v[56:57], v[178:179]
	v_pk_add_f32 v[50:51], v[50:51], v[180:181]
	v_pk_add_f32 v[52:53], v[52:53], v[182:183]
	v_cvt_pk_bf16_f32 v168, v62, v63
	v_cvt_pk_bf16_f32 v169, v64, v65
	v_cvt_pk_bf16_f32 v170, v58, v59
	v_cvt_pk_bf16_f32 v171, v60, v61
	v_cvt_pk_bf16_f32 v172, v54, v55
	v_cvt_pk_bf16_f32 v173, v56, v57
	v_cvt_pk_bf16_f32 v174, v50, v51
	v_cvt_pk_bf16_f32 v175, v52, v53
	v_mul_f32_e32 v163, v62, v62
	v_mul_f32_e32 v200, v63, v63
	v_fmac_f32_e32 v163, v64, v64
	v_fmac_f32_e32 v200, v65, v65
	v_fmac_f32_e32 v163, v58, v58
	v_fmac_f32_e32 v200, v59, v59
	v_fmac_f32_e32 v163, v60, v60
	v_fmac_f32_e32 v200, v61, v61
	v_fmac_f32_e32 v163, v54, v54
	v_fmac_f32_e32 v200, v55, v55
	v_fmac_f32_e32 v163, v56, v56
	v_fmac_f32_e32 v200, v57, v57
	v_fmac_f32_e32 v163, v50, v50
	v_fmac_f32_e32 v200, v51, v51
	v_fmac_f32_e32 v163, v52, v52
	v_fmac_f32_e32 v200, v53, v53
	ds_bpermute_b32 v62, v232, v62
	ds_bpermute_b32 v63, v232, v63
	ds_bpermute_b32 v64, v232, v64
	ds_bpermute_b32 v65, v232, v65
	ds_bpermute_b32 v58, v232, v58
	ds_bpermute_b32 v59, v232, v59
	ds_bpermute_b32 v60, v232, v60
	ds_bpermute_b32 v61, v232, v61
	ds_bpermute_b32 v54, v232, v54
	ds_bpermute_b32 v55, v232, v55
	ds_bpermute_b32 v56, v232, v56
	ds_bpermute_b32 v57, v232, v57
	ds_bpermute_b32 v50, v232, v50
	ds_bpermute_b32 v51, v232, v51
	ds_bpermute_b32 v52, v232, v52
	ds_bpermute_b32 v53, v232, v53
	ds_bpermute_b32 v168, v232, v168
	ds_bpermute_b32 v169, v232, v169
	ds_bpermute_b32 v170, v232, v170
	ds_bpermute_b32 v171, v232, v171
	ds_bpermute_b32 v172, v232, v172
	ds_bpermute_b32 v173, v232, v173
	ds_bpermute_b32 v174, v232, v174
	ds_bpermute_b32 v175, v232, v175
	s_waitcnt lgkmcnt(0)
	global_store_dwordx4 v233, v[62:65], s[44:45]
	global_store_dwordx4 v233, v[58:61], s[44:45] offset:16
	global_store_dwordx4 v233, v[54:57], s[44:45] offset:512
	global_store_dwordx4 v233, v[50:53], s[44:45] offset:528
	global_store_dwordx4 v234, v[168:171], s[6:7]
	global_store_dwordx4 v234, v[172:175], s[6:7] offset:256
	v_add_f32_e32 v50, v163, v200
	s_add_u32 s44, s44, 0x10000
	s_addc_u32 s45, s45, 0
	s_add_u32 s6, s6, 0x8000
	s_addc_u32 s7, s7, 0
	s_waitcnt vmcnt(26)
; __device__ __forceinline__ unsigned cvtpk(float lo, float hi) { f32x2 v = {lo, hi}; bf16x2_t b = __builtin_convertvector(v, bf16x2_t); return __builtin_bit_cast(unsigned, b); }
;     __device__ __forceinline__ void operator()(const f32x4 (&acc)[2][2][4][2], const pg8::Unit& u, int wr, int wc, int fr, int fq) const {
;     ...
;                     for (int bj = 0; bj < 2; ++bj) {
;                         const int col0 = u.pn * 256 + bj * 128 + wc * 32 + 8 * fq;
;                         const f32x4 h0 = *(const f32x4*)(src + col0) + acc[ai][bj][m][0];
;                         const f32x4 h1 = *(const f32x4*)(src + col0 + 4) + acc[ai][bj][m][1];
;                         *(f32x4*)(dst + col0) = h0; *(f32x4*)(dst + col0 + 4) = h1;
;                         if (P) { u32x4 w; w.x = cvtpk(h0[0], h0[1]); w.y = cvtpk(h0[2], h0[3]); w.z = cvtpk(h1[0], h1[1]); w.w = cvtpk(h1[2], h1[3]);
;                             *(u32x4*)(P + (size_t)grow * DM + col0) = w; }
;                         ss += (h0[0] * h0[0] + h0[1] * h0[1]) + (h0[2] * h0[2] + h0[3] * h0[3]) + (h1[0] * h1[0] + h1[1] * h1[1]) + (h1[2] * h1[2] + h1[3] * h1[3]);
;                     }
	v_pk_add_f32 v[46:47], v[46:47], v[184:185]
	v_pk_add_f32 v[48:49], v[48:49], v[186:187]
	v_pk_add_f32 v[42:43], v[42:43], v[188:189]
	v_pk_add_f32 v[44:45], v[44:45], v[190:191]
	v_pk_add_f32 v[38:39], v[38:39], v[192:193]
	v_pk_add_f32 v[40:41], v[40:41], v[194:195]
	v_pk_add_f32 v[34:35], v[34:35], v[196:197]
	v_pk_add_f32 v[36:37], v[36:37], v[198:199]
	v_cvt_pk_bf16_f32 v184, v46, v47
	v_cvt_pk_bf16_f32 v185, v48, v49
	v_cvt_pk_bf16_f32 v186, v42, v43
	v_cvt_pk_bf16_f32 v187, v44, v45
	v_cvt_pk_bf16_f32 v188, v38, v39
	v_cvt_pk_bf16_f32 v189, v40, v41
	v_cvt_pk_bf16_f32 v190, v34, v35
	v_cvt_pk_bf16_f32 v191, v36, v37
	v_mul_f32_e32 v163, v46, v46
	v_mul_f32_e32 v200, v47, v47
	v_fmac_f32_e32 v163, v48, v48
	v_fmac_f32_e32 v200, v49, v49
	v_fmac_f32_e32 v163, v42, v42
	v_fmac_f32_e32 v200, v43, v43
	v_fmac_f32_e32 v163, v44, v44
	v_fmac_f32_e32 v200, v45, v45
	v_fmac_f32_e32 v163, v38, v38
	v_fmac_f32_e32 v200, v39, v39
	v_fmac_f32_e32 v163, v40, v40
	v_fmac_f32_e32 v200, v41, v41
	v_fmac_f32_e32 v163, v34, v34
	v_fmac_f32_e32 v200, v35, v35
	v_fmac_f32_e32 v163, v36, v36
	v_fmac_f32_e32 v200, v37, v37
	ds_bpermute_b32 v46, v232, v46
	ds_bpermute_b32 v47, v232, v47
	ds_bpermute_b32 v48, v232, v48
	ds_bpermute_b32 v49, v232, v49
	ds_bpermute_b32 v42, v232, v42
	ds_bpermute_b32 v43, v232, v43
	ds_bpermute_b32 v44, v232, v44
	ds_bpermute_b32 v45, v232, v45
	ds_bpermute_b32 v38, v232, v38
	ds_bpermute_b32 v39, v232, v39
	ds_bpermute_b32 v40, v232, v40
	ds_bpermute_b32 v41, v232, v41
	ds_bpermute_b32 v34, v232, v34
	ds_bpermute_b32 v35, v232, v35
	ds_bpermute_b32 v36, v232, v36
	ds_bpermute_b32 v37, v232, v37
	ds_bpermute_b32 v184, v232, v184
	ds_bpermute_b32 v185, v232, v185
	ds_bpermute_b32 v186, v232, v186
	ds_bpermute_b32 v187, v232, v187
	ds_bpermute_b32 v188, v232, v188
	ds_bpermute_b32 v189, v232, v189
	ds_bpermute_b32 v190, v232, v190
	ds_bpermute_b32 v191, v232, v191
	s_waitcnt lgkmcnt(0)
	global_store_dwordx4 v233, v[46:49], s[44:45]
	global_store_dwordx4 v233, v[42:45], s[44:45] offset:16
	global_store_dwordx4 v233, v[38:41], s[44:45] offset:512
	global_store_dwordx4 v233, v[34:37], s[44:45] offset:528
	global_store_dwordx4 v234, v[184:187], s[6:7]
	global_store_dwordx4 v234, v[188:191], s[6:7] offset:256
	v_add_f32_e32 v34, v163, v200
	s_add_u32 s44, s44, 0x10000
	s_addc_u32 s45, s45, 0
	s_add_u32 s6, s6, 0x8000
	s_addc_u32 s7, s7, 0
	s_waitcnt vmcnt(22)
	v_pk_add_f32 v[28:29], v[28:29], v[216:217]
	v_pk_add_f32 v[30:31], v[30:31], v[218:219]
	v_pk_add_f32 v[24:25], v[24:25], v[220:221]
	v_pk_add_f32 v[26:27], v[26:27], v[222:223]
	v_pk_add_f32 v[20:21], v[20:21], v[224:225]
	v_pk_add_f32 v[22:23], v[22:23], v[226:227]
	v_pk_add_f32 v[16:17], v[16:17], v[228:229]
	v_pk_add_f32 v[18:19], v[18:19], v[230:231]
	v_cvt_pk_bf16_f32 v216, v28, v29
	v_cvt_pk_bf16_f32 v217, v30, v31
	v_cvt_pk_bf16_f32 v218, v24, v25
	v_cvt_pk_bf16_f32 v219, v26, v27
	v_cvt_pk_bf16_f32 v220, v20, v21
	v_cvt_pk_bf16_f32 v221, v22, v23
	v_cvt_pk_bf16_f32 v222, v16, v17
	v_cvt_pk_bf16_f32 v223, v18, v19
	v_mul_f32_e32 v163, v28, v28
	v_mul_f32_e32 v200, v29, v29
	v_fmac_f32_e32 v163, v30, v30
	v_fmac_f32_e32 v200, v31, v31
	v_fmac_f32_e32 v163, v24, v24
	v_fmac_f32_e32 v200, v25, v25
	v_fmac_f32_e32 v163, v26, v26
	v_fmac_f32_e32 v200, v27, v27
	v_fmac_f32_e32 v163, v20, v20
	v_fmac_f32_e32 v200, v21, v21
	v_fmac_f32_e32 v163, v22, v22
	v_fmac_f32_e32 v200, v23, v23
	v_fmac_f32_e32 v163, v16, v16
	v_fmac_f32_e32 v200, v17, v17
	v_fmac_f32_e32 v163, v18, v18
	v_fmac_f32_e32 v200, v19, v19
	ds_bpermute_b32 v28, v232, v28
	ds_bpermute_b32 v29, v232, v29
	ds_bpermute_b32 v30, v232, v30
	ds_bpermute_b32 v31, v232, v31
	ds_bpermute_b32 v24, v232, v24
	ds_bpermute_b32 v25, v232, v25
	ds_bpermute_b32 v26, v232, v26
	ds_bpermute_b32 v27, v232, v27
	ds_bpermute_b32 v20, v232, v20
	ds_bpermute_b32 v21, v232, v21
	ds_bpermute_b32 v22, v232, v22
	ds_bpermute_b32 v23, v232, v23
	ds_bpermute_b32 v16, v232, v16
	ds_bpermute_b32 v17, v232, v17
	ds_bpermute_b32 v18, v232, v18
	ds_bpermute_b32 v19, v232, v19
	ds_bpermute_b32 v216, v232, v216
	ds_bpermute_b32 v217, v232, v217
	ds_bpermute_b32 v218, v232, v218
	ds_bpermute_b32 v219, v232, v219
	ds_bpermute_b32 v220, v232, v220
	ds_bpermute_b32 v221, v232, v221
	ds_bpermute_b32 v222, v232, v222
	ds_bpermute_b32 v223, v232, v223
	s_waitcnt lgkmcnt(0)
	global_store_dwordx4 v233, v[28:31], s[44:45]
	global_store_dwordx4 v233, v[24:27], s[44:45] offset:16
	global_store_dwordx4 v233, v[20:23], s[44:45] offset:512
	global_store_dwordx4 v233, v[16:19], s[44:45] offset:528
	global_store_dwordx4 v234, v[216:219], s[6:7]
	global_store_dwordx4 v234, v[220:223], s[6:7] offset:256
	v_add_f32_e32 v16, v163, v200
	s_add_u32 s44, s44, 0x10000
	s_addc_u32 s45, s45, 0
	s_add_u32 s6, s6, 0x8000
	s_addc_u32 s7, s7, 0
	s_waitcnt vmcnt(18)
; __device__ __forceinline__ unsigned cvtpk(float lo, float hi) { f32x2 v = {lo, hi}; bf16x2_t b = __builtin_convertvector(v, bf16x2_t); return __builtin_bit_cast(unsigned, b); }
;     __device__ __forceinline__ void operator()(const f32x4 (&acc)[2][2][4][2], const pg8::Unit& u, int wr, int wc, int fr, int fq) const {
;     ...
;                     for (int bj = 0; bj < 2; ++bj) {
;                         const int col0 = u.pn * 256 + bj * 128 + wc * 32 + 8 * fq;
;                         const f32x4 h0 = *(const f32x4*)(src + col0) + acc[ai][bj][m][0];
;                         const f32x4 h1 = *(const f32x4*)(src + col0 + 4) + acc[ai][bj][m][1];
;                         *(f32x4*)(dst + col0) = h0; *(f32x4*)(dst + col0 + 4) = h1;
;                         if (P) { u32x4 w; w.x = cvtpk(h0[0], h0[1]); w.y = cvtpk(h0[2], h0[3]); w.z = cvtpk(h1[0], h1[1]); w.w = cvtpk(h1[2], h1[3]);
;                             *(u32x4*)(P + (size_t)grow * DM + col0) = w; }
;                         ss += (h0[0] * h0[0] + h0[1] * h0[1]) + (h0[2] * h0[2] + h0[3] * h0[3]) + (h1[0] * h1[0] + h1[1] * h1[1]) + (h1[2] * h1[2] + h1[3] * h1[3]);
;                     }
;                 }
;                 ss += __shfl_xor(ss, 16); ss += __shfl_xor(ss, 32);
;                 if (ok && fq == 0 && rowss_next) atomicAdd(rowss_next + grow, (u64)(ss * SS_SCALE));
	v_pk_add_f32 v[12:13], v[12:13], v[142:143]
	v_pk_add_f32 v[14:15], v[14:15], v[144:145]
	v_pk_add_f32 v[8:9], v[8:9], v[146:147]
	v_pk_add_f32 v[10:11], v[10:11], v[148:149]
	v_pk_add_f32 v[4:5], v[4:5], v[158:159]
	v_pk_add_f32 v[6:7], v[6:7], v[160:161]
	v_pk_add_f32 v[0:1], v[0:1], v[204:205]
	v_pk_add_f32 v[2:3], v[2:3], v[206:207]
	v_cvt_pk_bf16_f32 v142, v12, v13
	v_cvt_pk_bf16_f32 v143, v14, v15
	v_cvt_pk_bf16_f32 v144, v8, v9
	v_cvt_pk_bf16_f32 v145, v10, v11
	v_cvt_pk_bf16_f32 v146, v4, v5
	v_cvt_pk_bf16_f32 v147, v6, v7
	v_cvt_pk_bf16_f32 v148, v0, v1
	v_cvt_pk_bf16_f32 v149, v2, v3
	v_mul_f32_e32 v163, v12, v12
	v_mul_f32_e32 v200, v13, v13
	v_fmac_f32_e32 v163, v14, v14
	v_fmac_f32_e32 v200, v15, v15
	v_fmac_f32_e32 v163, v8, v8
	v_fmac_f32_e32 v200, v9, v9
	v_fmac_f32_e32 v163, v10, v10
	v_fmac_f32_e32 v200, v11, v11
	v_fmac_f32_e32 v163, v4, v4
	v_fmac_f32_e32 v200, v5, v5
	v_fmac_f32_e32 v163, v6, v6
	v_fmac_f32_e32 v200, v7, v7
	v_fmac_f32_e32 v163, v0, v0
	v_fmac_f32_e32 v200, v1, v1
	v_fmac_f32_e32 v163, v2, v2
	v_fmac_f32_e32 v200, v3, v3
	ds_bpermute_b32 v12, v232, v12
	ds_bpermute_b32 v13, v232, v13
	ds_bpermute_b32 v14, v232, v14
	ds_bpermute_b32 v15, v232, v15
	ds_bpermute_b32 v8, v232, v8
	ds_bpermute_b32 v9, v232, v9
	ds_bpermute_b32 v10, v232, v10
	ds_bpermute_b32 v11, v232, v11
	ds_bpermute_b32 v4, v232, v4
	ds_bpermute_b32 v5, v232, v5
	ds_bpermute_b32 v6, v232, v6
	ds_bpermute_b32 v7, v232, v7
	ds_bpermute_b32 v0, v232, v0
	ds_bpermute_b32 v1, v232, v1
	ds_bpermute_b32 v2, v232, v2
	ds_bpermute_b32 v3, v232, v3
	ds_bpermute_b32 v142, v232, v142
	ds_bpermute_b32 v143, v232, v143
	ds_bpermute_b32 v144, v232, v144
	ds_bpermute_b32 v145, v232, v145
	ds_bpermute_b32 v146, v232, v146
	ds_bpermute_b32 v147, v232, v147
	ds_bpermute_b32 v148, v232, v148
	ds_bpermute_b32 v149, v232, v149
	s_waitcnt lgkmcnt(0)
	global_store_dwordx4 v233, v[12:15], s[44:45]
	global_store_dwordx4 v233, v[8:11], s[44:45] offset:16
	global_store_dwordx4 v233, v[4:7], s[44:45] offset:512
	global_store_dwordx4 v233, v[0:3], s[44:45] offset:528
	global_store_dwordx4 v234, v[142:145], s[6:7]
	global_store_dwordx4 v234, v[146:149], s[6:7] offset:256
	v_add_f32_e32 v0, v163, v200
	v_mbcnt_lo_u32_b32 v201, -1, 0
	v_mbcnt_hi_u32_b32 v201, -1, v201
	v_xor_b32_e32 v208, 16, v201
	v_xor_b32_e32 v209, 32, v201
	v_lshlrev_b32_e32 v208, 2, v208
	v_lshlrev_b32_e32 v209, 2, v209
	ds_bpermute_b32 v115, v208, v114
	ds_bpermute_b32 v99, v208, v98
	ds_bpermute_b32 v83, v208, v82
	ds_bpermute_b32 v67, v208, v66
	ds_bpermute_b32 v51, v208, v50
	ds_bpermute_b32 v35, v208, v34
	ds_bpermute_b32 v17, v208, v16
	ds_bpermute_b32 v1, v208, v0
	s_waitcnt lgkmcnt(0)
	v_add_f32_e32 v114, v114, v115
	v_add_f32_e32 v98, v98, v99
	v_add_f32_e32 v82, v82, v83
	v_add_f32_e32 v66, v66, v67
	v_add_f32_e32 v50, v50, v51
	v_add_f32_e32 v34, v34, v35
	v_add_f32_e32 v16, v16, v17
	v_add_f32_e32 v0, v0, v1
	ds_bpermute_b32 v115, v209, v114
	ds_bpermute_b32 v99, v209, v98
	ds_bpermute_b32 v83, v209, v82
	ds_bpermute_b32 v67, v209, v66
	ds_bpermute_b32 v51, v209, v50
	ds_bpermute_b32 v35, v209, v34
	ds_bpermute_b32 v17, v209, v16
	ds_bpermute_b32 v1, v209, v0
	s_waitcnt lgkmcnt(0)
	v_add_f32_e32 v114, v114, v115
	v_add_f32_e32 v98, v98, v99
	v_add_f32_e32 v82, v82, v83
	v_add_f32_e32 v66, v66, v67
	v_add_f32_e32 v50, v50, v51
	v_add_f32_e32 v34, v34, v35
	v_add_f32_e32 v16, v16, v17
	v_add_f32_e32 v0, v0, v1
	s_and_saveexec_b64 s[42:43], s[2:3]
	v_mul_f32_e32 v114, 0x49800000, v114
	v_trunc_f32_e32 v114, v114
	v_mul_f32_e32 v115, 0x2f800000, v114
	v_floor_f32_e32 v115, v115
	v_fmac_f32_e32 v114, 0xcf800000, v115
	v_cvt_u32_f32_e32 v116, v114
	v_cvt_u32_f32_e32 v117, v115
	global_atomic_add_x2 v162, v[116:117], s[8:9]
	v_mul_f32_e32 v98, 0x49800000, v98
	v_trunc_f32_e32 v98, v98
	v_mul_f32_e32 v99, 0x2f800000, v98
	v_floor_f32_e32 v99, v99
	v_fmac_f32_e32 v98, 0xcf800000, v99
	v_cvt_u32_f32_e32 v100, v98
	v_cvt_u32_f32_e32 v101, v99
	global_atomic_add_x2 v162, v[100:101], s[8:9] offset:128
	v_mul_f32_e32 v82, 0x49800000, v82
	v_trunc_f32_e32 v82, v82
	v_mul_f32_e32 v83, 0x2f800000, v82
	v_floor_f32_e32 v83, v83
	v_fmac_f32_e32 v82, 0xcf800000, v83
	v_cvt_u32_f32_e32 v84, v82
	v_cvt_u32_f32_e32 v85, v83
	global_atomic_add_x2 v162, v[84:85], s[8:9] offset:256
	v_mul_f32_e32 v66, 0x49800000, v66
	v_trunc_f32_e32 v66, v66
	v_mul_f32_e32 v67, 0x2f800000, v66
	v_floor_f32_e32 v67, v67
	v_fmac_f32_e32 v66, 0xcf800000, v67
	v_cvt_u32_f32_e32 v68, v66
	v_cvt_u32_f32_e32 v69, v67
	global_atomic_add_x2 v162, v[68:69], s[8:9] offset:384
	v_mul_f32_e32 v50, 0x49800000, v50
	v_trunc_f32_e32 v50, v50
	v_mul_f32_e32 v51, 0x2f800000, v50
	v_floor_f32_e32 v51, v51
	v_fmac_f32_e32 v50, 0xcf800000, v51
	v_cvt_u32_f32_e32 v52, v50
	v_cvt_u32_f32_e32 v53, v51
	global_atomic_add_x2 v162, v[52:53], s[8:9] offset:1024
	v_mul_f32_e32 v34, 0x49800000, v34
	v_trunc_f32_e32 v34, v34
	v_mul_f32_e32 v35, 0x2f800000, v34
	v_floor_f32_e32 v35, v35
	v_fmac_f32_e32 v34, 0xcf800000, v35
	v_cvt_u32_f32_e32 v36, v34
	v_cvt_u32_f32_e32 v37, v35
	global_atomic_add_x2 v162, v[36:37], s[8:9] offset:1152
	v_mul_f32_e32 v16, 0x49800000, v16
	v_trunc_f32_e32 v16, v16
	v_mul_f32_e32 v17, 0x2f800000, v16
	v_floor_f32_e32 v17, v17
	v_fmac_f32_e32 v16, 0xcf800000, v17
	v_cvt_u32_f32_e32 v18, v16
	v_cvt_u32_f32_e32 v19, v17
	global_atomic_add_x2 v162, v[18:19], s[8:9] offset:1280
	v_mul_f32_e32 v0, 0x49800000, v0
	v_trunc_f32_e32 v0, v0
	v_mul_f32_e32 v1, 0x2f800000, v0
	v_floor_f32_e32 v1, v1
	v_fmac_f32_e32 v0, 0xcf800000, v1
	v_cvt_u32_f32_e32 v2, v0
	v_cvt_u32_f32_e32 v3, v1
	global_atomic_add_x2 v162, v[2:3], s[8:9] offset:1408
	s_mov_b64 exec, s[42:43]
	s_movk_i32 s75, 0x80
	s_mov_b32 s76, 0x7f807f81
	s_movk_i32 s77, 0x5b
	s_branch .Lepi_done_ao

; __global__ void __launch_bounds__(512, 2) fwd_megakernel(Args a_unused) {
;     ...
;     for (int layer = layer_lo; layer < layer_hi; ++layer) {
;         if ((layer & 1) == 0) {
.Ltramp_418:
	s_branch .LBB0_418

; __device__ __forceinline__ unsigned cvtpk(float lo, float hi) { f32x2 v = {lo, hi}; bf16x2_t b = __builtin_convertvector(v, bf16x2_t); return __builtin_bit_cast(unsigned, b); }
;     __device__ __forceinline__ void operator()(const f32x4 (&acc)[2][2][4][2], const pg8::Unit& u, int wr, int wc, int fr, int fq) const {
;     ...
;                 const int grow = row_base + u.pm * 256 + ai * 128 + wr * 64 + m * 16 + fr;
;                 const bool ok = grow < MREAL;
;                 float ss = 0.f;
;                 if (ok) {
;                     const float* src; float* dst;
;                     if (grow < ROWS_P) { src = srcA + (size_t)grow * DM; dst = dstMain + (size_t)grow * DM; }
;                     else if (grow < ROWS_MAIN) { src = srcB + (size_t)(grow - ROWS_P) * DM; dst = dstMain + (size_t)grow * DM; }
;                     else { const int mr = grow - ROWS_MAIN; src = srcM + (size_t)(mr & meta_mask) * DM; dst = dstM + (size_t)mr * DM; }
; #pragma unroll
;                     for (int bj = 0; bj < 2; ++bj) {
;                         const int col0 = u.pn * 256 + bj * 128 + wc * 32 + 8 * fq;
;                         const f32x4 h0 = *(const f32x4*)(src + col0) + acc[ai][bj][m][0];
;                         const f32x4 h1 = *(const f32x4*)(src + col0 + 4) + acc[ai][bj][m][1];
;                         *(f32x4*)(dst + col0) = h0; *(f32x4*)(dst + col0 + 4) = h1;
;                         if (P) { u32x4 w; w.x = cvtpk(h0[0], h0[1]); w.y = cvtpk(h0[2], h0[3]); w.z = cvtpk(h1[0], h1[1]); w.w = cvtpk(h1[2], h1[3]);
;                             *(u32x4*)(P + (size_t)grow * DM + col0) = w; }
;                         ss += (h0[0] * h0[0] + h0[1] * h0[1]) + (h0[2] * h0[2] + h0[3] * h0[3]) + (h1[0] * h1[0] + h1[1] * h1[1]) + (h1[2] * h1[2] + h1[3] * h1[3]);
;                     }
;                 }
;                 ss += __shfl_xor(ss, 16); ss += __shfl_xor(ss, 32);
;                 if (ok && fq == 0 && rowss_next) atomicAdd(rowss_next + grow, (u64)(ss * SS_SCALE));
.LBB0_2135:
	s_lshl_b32 vcc_lo, s8, 8
	s_add_i32 vcc_lo, vcc_lo, s66
	s_cmp_lt_u32 vcc_lo, 0x18000
	s_cbranch_scc0 .Lepi_old_dn
	s_cmp_lg_u64 s[18:19], 0
	s_cbranch_scc0 .Lepi_old_dn
	s_cmp_eq_u64 s[16:17], 0
	s_cbranch_scc0 .Lepi_old_dn
	s_lshl_b32 vcc_hi, s6, 10
	s_lshl_b32 s8, vcc_lo, 3
	s_add_u32 s8, s34, s8
	s_addc_u32 s9, s35, 0
	s_lshl_b32 s6, vcc_lo, 12
	s_add_u32 vcc_hi, vcc_hi, s6
	s_add_u32 s50, s12, vcc_hi
	s_addc_u32 s51, s13, 0
	s_lshr_b32 s6, vcc_hi, 1
	s_add_u32 s6, s30, s6
	s_addc_u32 s7, s31, 0
	s_cmp_lt_u32 vcc_lo, 0x8000
	s_cselect_b32 s48, s12, s36
	s_cselect_b32 s49, s13, s37
	s_cselect_b32 vcc_lo, 0, 0x8000000
	s_sub_u32 vcc_hi, vcc_hi, vcc_lo
	s_add_u32 s48, s48, vcc_hi
	s_addc_u32 s49, s49, 0
	v_lshlrev_b32_e32 v150, 12, v164
	v_lshl_add_u32 v150, v166, 2, v150
	v_lshrrev_b32_e32 v151, 1, v150
	v_lshlrev_b32_e32 v162, 3, v164
	v_mbcnt_lo_u32_b32 v235, -1, 0
	v_mbcnt_hi_u32_b32 v235, -1, v235
	v_and_b32_e32 v232, 3, v235
	v_lshlrev_b32_e32 v232, 6, v232
	v_and_b32_e32 v236, 60, v235
	v_or_b32_e32 v232, v232, v236
	v_lshrrev_b32_e32 v236, 2, v235
	v_and_b32_e32 v237, 15, v235
	v_sub_u32_e32 v236, v236, v237
	v_lshl_add_u32 v233, v236, 12, v150
	v_and_b32_e32 v236, 3, v235
	v_lshrrev_b32_e32 v237, 4, v235
	v_sub_u32_e32 v236, v236, v237
	v_lshl_add_u32 v233, v236, 5, v233
	v_lshrrev_b32_e32 v234, 1, v233
	global_load_dwordx4 v[168:171], v150, s[48:49]
	global_load_dwordx4 v[172:175], v150, s[48:49] offset:16
	global_load_dwordx4 v[176:179], v150, s[48:49] offset:512
	global_load_dwordx4 v[180:183], v150, s[48:49] offset:528
	s_add_u32 s48, s48, 0x10000
	s_addc_u32 s49, s49, 0
	global_load_dwordx4 v[184:187], v150, s[48:49]
	global_load_dwordx4 v[188:191], v150, s[48:49] offset:16
	global_load_dwordx4 v[192:195], v150, s[48:49] offset:512
	global_load_dwordx4 v[196:199], v150, s[48:49] offset:528
	s_add_u32 s48, s48, 0x10000
	s_addc_u32 s49, s49, 0
	global_load_dwordx4 v[216:219], v150, s[48:49]
	global_load_dwordx4 v[220:223], v150, s[48:49] offset:16
	global_load_dwordx4 v[224:227], v150, s[48:49] offset:512
	global_load_dwordx4 v[228:231], v150, s[48:49] offset:528
	s_add_u32 s48, s48, 0x10000
	s_addc_u32 s49, s49, 0
	global_load_dwordx4 v[142:145], v150, s[48:49]
	global_load_dwordx4 v[146:149], v150, s[48:49] offset:16
	global_load_dwordx4 v[158:161], v150, s[48:49] offset:512
	global_load_dwordx4 v[204:207], v150, s[48:49] offset:528
	s_add_u32 s48, s48, 0x50000
	s_addc_u32 s49, s49, 0
	s_waitcnt vmcnt(12)
	v_pk_add_f32 v[126:127], v[126:127], v[168:169]
	v_pk_add_f32 v[128:129], v[128:129], v[170:171]
	v_pk_add_f32 v[122:123], v[122:123], v[172:173]
	v_pk_add_f32 v[124:125], v[124:125], v[174:175]
	v_pk_add_f32 v[118:119], v[118:119], v[176:177]
	v_pk_add_f32 v[120:121], v[120:121], v[178:179]
	v_pk_add_f32 v[114:115], v[114:115], v[180:181]
	v_pk_add_f32 v[116:117], v[116:117], v[182:183]
	v_cvt_pk_bf16_f32 v168, v126, v127
	v_cvt_pk_bf16_f32 v169, v128, v129
	v_cvt_pk_bf16_f32 v170, v122, v123
	v_cvt_pk_bf16_f32 v171, v124, v125
	v_cvt_pk_bf16_f32 v172, v118, v119
	v_cvt_pk_bf16_f32 v173, v120, v121
	v_cvt_pk_bf16_f32 v174, v114, v115
	v_cvt_pk_bf16_f32 v175, v116, v117
	v_mul_f32_e32 v163, v126, v126
	v_mul_f32_e32 v200, v127, v127
	v_fmac_f32_e32 v163, v128, v128
	v_fmac_f32_e32 v200, v129, v129
	v_fmac_f32_e32 v163, v122, v122
	v_fmac_f32_e32 v200, v123, v123
	v_fmac_f32_e32 v163, v124, v124
	v_fmac_f32_e32 v200, v125, v125
	v_fmac_f32_e32 v163, v118, v118
	v_fmac_f32_e32 v200, v119, v119
	v_fmac_f32_e32 v163, v120, v120
	v_fmac_f32_e32 v200, v121, v121
	v_fmac_f32_e32 v163, v114, v114
	v_fmac_f32_e32 v200, v115, v115
	v_fmac_f32_e32 v163, v116, v116
	v_fmac_f32_e32 v200, v117, v117
	ds_bpermute_b32 v126, v232, v126
	ds_bpermute_b32 v127, v232, v127
	ds_bpermute_b32 v128, v232, v128
	ds_bpermute_b32 v129, v232, v129
	ds_bpermute_b32 v122, v232, v122
	ds_bpermute_b32 v123, v232, v123
	ds_bpermute_b32 v124, v232, v124
	ds_bpermute_b32 v125, v232, v125
	ds_bpermute_b32 v118, v232, v118
	ds_bpermute_b32 v119, v232, v119
	ds_bpermute_b32 v120, v232, v120
	ds_bpermute_b32 v121, v232, v121
	ds_bpermute_b32 v114, v232, v114
	ds_bpermute_b32 v115, v232, v115
	ds_bpermute_b32 v116, v232, v116
	ds_bpermute_b32 v117, v232, v117
	ds_bpermute_b32 v168, v232, v168
	ds_bpermute_b32 v169, v232, v169
	ds_bpermute_b32 v170, v232, v170
	ds_bpermute_b32 v171, v232, v171
	ds_bpermute_b32 v172, v232, v172
	ds_bpermute_b32 v173, v232, v173
	ds_bpermute_b32 v174, v232, v174
	ds_bpermute_b32 v175, v232, v175
	s_waitcnt lgkmcnt(0)
	global_store_dwordx4 v233, v[126:129], s[50:51]
	global_store_dwordx4 v233, v[122:125], s[50:51] offset:16
	global_store_dwordx4 v233, v[118:121], s[50:51] offset:512
	global_store_dwordx4 v233, v[114:117], s[50:51] offset:528
	global_store_dwordx4 v234, v[168:171], s[6:7]
	global_store_dwordx4 v234, v[172:175], s[6:7] offset:256
	v_add_f32_e32 v114, v163, v200
	s_add_u32 s50, s50, 0x10000
	s_addc_u32 s51, s51, 0
	s_add_u32 s6, s6, 0x8000
	s_addc_u32 s7, s7, 0
	global_load_dwordx4 v[168:171], v150, s[48:49]
	global_load_dwordx4 v[172:175], v150, s[48:49] offset:16
	global_load_dwordx4 v[176:179], v150, s[48:49] offset:512
	global_load_dwordx4 v[180:183], v150, s[48:49] offset:528
	s_add_u32 s48, s48, 0x10000
	s_addc_u32 s49, s49, 0
	s_waitcnt vmcnt(18)
; __device__ __forceinline__ unsigned cvtpk(float lo, float hi) { f32x2 v = {lo, hi}; bf16x2_t b = __builtin_convertvector(v, bf16x2_t); return __builtin_bit_cast(unsigned, b); }
;     __device__ __forceinline__ void operator()(const f32x4 (&acc)[2][2][4][2], const pg8::Unit& u, int wr, int wc, int fr, int fq) const {
;     ...
;                     for (int bj = 0; bj < 2; ++bj) {
;                         const int col0 = u.pn * 256 + bj * 128 + wc * 32 + 8 * fq;
;                         const f32x4 h0 = *(const f32x4*)(src + col0) + acc[ai][bj][m][0];
;                         const f32x4 h1 = *(const f32x4*)(src + col0 + 4) + acc[ai][bj][m][1];
;                         *(f32x4*)(dst + col0) = h0; *(f32x4*)(dst + col0 + 4) = h1;
;                         if (P) { u32x4 w; w.x = cvtpk(h0[0], h0[1]); w.y = cvtpk(h0[2], h0[3]); w.z = cvtpk(h1[0], h1[1]); w.w = cvtpk(h1[2], h1[3]);
;                             *(u32x4*)(P + (size_t)grow * DM + col0) = w; }
;                         ss += (h0[0] * h0[0] + h0[1] * h0[1]) + (h0[2] * h0[2] + h0[3] * h0[3]) + (h1[0] * h1[0] + h1[1] * h1[1]) + (h1[2] * h1[2] + h1[3] * h1[3]);
;                     }
	v_pk_add_f32 v[110:111], v[110:111], v[184:185]
	v_pk_add_f32 v[112:113], v[112:113], v[186:187]
	v_pk_add_f32 v[106:107], v[106:107], v[188:189]
	v_pk_add_f32 v[108:109], v[108:109], v[190:191]
	v_pk_add_f32 v[102:103], v[102:103], v[192:193]
	v_pk_add_f32 v[104:105], v[104:105], v[194:195]
	v_pk_add_f32 v[98:99], v[98:99], v[196:197]
	v_pk_add_f32 v[100:101], v[100:101], v[198:199]
	v_cvt_pk_bf16_f32 v184, v110, v111
	v_cvt_pk_bf16_f32 v185, v112, v113
	v_cvt_pk_bf16_f32 v186, v106, v107
	v_cvt_pk_bf16_f32 v187, v108, v109
	v_cvt_pk_bf16_f32 v188, v102, v103
	v_cvt_pk_bf16_f32 v189, v104, v105
	v_cvt_pk_bf16_f32 v190, v98, v99
	v_cvt_pk_bf16_f32 v191, v100, v101
	v_mul_f32_e32 v163, v110, v110
	v_mul_f32_e32 v200, v111, v111
	v_fmac_f32_e32 v163, v112, v112
	v_fmac_f32_e32 v200, v113, v113
	v_fmac_f32_e32 v163, v106, v106
	v_fmac_f32_e32 v200, v107, v107
	v_fmac_f32_e32 v163, v108, v108
	v_fmac_f32_e32 v200, v109, v109
	v_fmac_f32_e32 v163, v102, v102
	v_fmac_f32_e32 v200, v103, v103
	v_fmac_f32_e32 v163, v104, v104
	v_fmac_f32_e32 v200, v105, v105
	v_fmac_f32_e32 v163, v98, v98
	v_fmac_f32_e32 v200, v99, v99
	v_fmac_f32_e32 v163, v100, v100
	v_fmac_f32_e32 v200, v101, v101
	ds_bpermute_b32 v110, v232, v110
	ds_bpermute_b32 v111, v232, v111
	ds_bpermute_b32 v112, v232, v112
	ds_bpermute_b32 v113, v232, v113
	ds_bpermute_b32 v106, v232, v106
	ds_bpermute_b32 v107, v232, v107
	ds_bpermute_b32 v108, v232, v108
	ds_bpermute_b32 v109, v232, v109
	ds_bpermute_b32 v102, v232, v102
	ds_bpermute_b32 v103, v232, v103
	ds_bpermute_b32 v104, v232, v104
	ds_bpermute_b32 v105, v232, v105
	ds_bpermute_b32 v98, v232, v98
	ds_bpermute_b32 v99, v232, v99
	ds_bpermute_b32 v100, v232, v100
	ds_bpermute_b32 v101, v232, v101
	ds_bpermute_b32 v184, v232, v184
	ds_bpermute_b32 v185, v232, v185
	ds_bpermute_b32 v186, v232, v186
	ds_bpermute_b32 v187, v232, v187
	ds_bpermute_b32 v188, v232, v188
	ds_bpermute_b32 v189, v232, v189
	ds_bpermute_b32 v190, v232, v190
	ds_bpermute_b32 v191, v232, v191
	s_waitcnt lgkmcnt(0)
	global_store_dwordx4 v233, v[110:113], s[50:51]
	global_store_dwordx4 v233, v[106:109], s[50:51] offset:16
	global_store_dwordx4 v233, v[102:105], s[50:51] offset:512
	global_store_dwordx4 v233, v[98:101], s[50:51] offset:528
	global_store_dwordx4 v234, v[184:187], s[6:7]
	global_store_dwordx4 v234, v[188:191], s[6:7] offset:256
	v_add_f32_e32 v98, v163, v200
	s_add_u32 s50, s50, 0x10000
	s_addc_u32 s51, s51, 0
	s_add_u32 s6, s6, 0x8000
	s_addc_u32 s7, s7, 0
	global_load_dwordx4 v[184:187], v150, s[48:49]
	global_load_dwordx4 v[188:191], v150, s[48:49] offset:16
	global_load_dwordx4 v[192:195], v150, s[48:49] offset:512
	global_load_dwordx4 v[196:199], v150, s[48:49] offset:528
	s_add_u32 s48, s48, 0x10000
	s_addc_u32 s49, s49, 0
	s_waitcnt vmcnt(24)
	v_pk_add_f32 v[94:95], v[94:95], v[216:217]
	v_pk_add_f32 v[96:97], v[96:97], v[218:219]
	v_pk_add_f32 v[90:91], v[90:91], v[220:221]
	v_pk_add_f32 v[92:93], v[92:93], v[222:223]
	v_pk_add_f32 v[86:87], v[86:87], v[224:225]
	v_pk_add_f32 v[88:89], v[88:89], v[226:227]
	v_pk_add_f32 v[82:83], v[82:83], v[228:229]
	v_pk_add_f32 v[84:85], v[84:85], v[230:231]
	v_cvt_pk_bf16_f32 v216, v94, v95
	v_cvt_pk_bf16_f32 v217, v96, v97
	v_cvt_pk_bf16_f32 v218, v90, v91
	v_cvt_pk_bf16_f32 v219, v92, v93
	v_cvt_pk_bf16_f32 v220, v86, v87
	v_cvt_pk_bf16_f32 v221, v88, v89
	v_cvt_pk_bf16_f32 v222, v82, v83
	v_cvt_pk_bf16_f32 v223, v84, v85
	v_mul_f32_e32 v163, v94, v94
	v_mul_f32_e32 v200, v95, v95
	v_fmac_f32_e32 v163, v96, v96
	v_fmac_f32_e32 v200, v97, v97
	v_fmac_f32_e32 v163, v90, v90
	v_fmac_f32_e32 v200, v91, v91
	v_fmac_f32_e32 v163, v92, v92
	v_fmac_f32_e32 v200, v93, v93
	v_fmac_f32_e32 v163, v86, v86
	v_fmac_f32_e32 v200, v87, v87
	v_fmac_f32_e32 v163, v88, v88
	v_fmac_f32_e32 v200, v89, v89
	v_fmac_f32_e32 v163, v82, v82
	v_fmac_f32_e32 v200, v83, v83
	v_fmac_f32_e32 v163, v84, v84
	v_fmac_f32_e32 v200, v85, v85
	ds_bpermute_b32 v94, v232, v94
	ds_bpermute_b32 v95, v232, v95
	ds_bpermute_b32 v96, v232, v96
	ds_bpermute_b32 v97, v232, v97
	ds_bpermute_b32 v90, v232, v90
	ds_bpermute_b32 v91, v232, v91
	ds_bpermute_b32 v92, v232, v92
	ds_bpermute_b32 v93, v232, v93
	ds_bpermute_b32 v86, v232, v86
	ds_bpermute_b32 v87, v232, v87
	ds_bpermute_b32 v88, v232, v88
	ds_bpermute_b32 v89, v232, v89
	ds_bpermute_b32 v82, v232, v82
	ds_bpermute_b32 v83, v232, v83
	ds_bpermute_b32 v84, v232, v84
	ds_bpermute_b32 v85, v232, v85
	ds_bpermute_b32 v216, v232, v216
	ds_bpermute_b32 v217, v232, v217
	ds_bpermute_b32 v218, v232, v218
	ds_bpermute_b32 v219, v232, v219
	ds_bpermute_b32 v220, v232, v220
	ds_bpermute_b32 v221, v232, v221
	ds_bpermute_b32 v222, v232, v222
	ds_bpermute_b32 v223, v232, v223
	s_waitcnt lgkmcnt(0)
	global_store_dwordx4 v233, v[94:97], s[50:51]
	global_store_dwordx4 v233, v[90:93], s[50:51] offset:16
	global_store_dwordx4 v233, v[86:89], s[50:51] offset:512
	global_store_dwordx4 v233, v[82:85], s[50:51] offset:528
	global_store_dwordx4 v234, v[216:219], s[6:7]
	global_store_dwordx4 v234, v[220:223], s[6:7] offset:256
	v_add_f32_e32 v82, v163, v200
	s_add_u32 s50, s50, 0x10000
	s_addc_u32 s51, s51, 0
	s_add_u32 s6, s6, 0x8000
	s_addc_u32 s7, s7, 0
	global_load_dwordx4 v[216:219], v150, s[48:49]
	global_load_dwordx4 v[220:223], v150, s[48:49] offset:16
	global_load_dwordx4 v[224:227], v150, s[48:49] offset:512
	global_load_dwordx4 v[228:231], v150, s[48:49] offset:528
	s_add_u32 s48, s48, 0x10000
	s_addc_u32 s49, s49, 0
	s_waitcnt vmcnt(30)
; __device__ __forceinline__ unsigned cvtpk(float lo, float hi) { f32x2 v = {lo, hi}; bf16x2_t b = __builtin_convertvector(v, bf16x2_t); return __builtin_bit_cast(unsigned, b); }
;     __device__ __forceinline__ void operator()(const f32x4 (&acc)[2][2][4][2], const pg8::Unit& u, int wr, int wc, int fr, int fq) const {
;     ...
;                     for (int bj = 0; bj < 2; ++bj) {
;                         const int col0 = u.pn * 256 + bj * 128 + wc * 32 + 8 * fq;
;                         const f32x4 h0 = *(const f32x4*)(src + col0) + acc[ai][bj][m][0];
;                         const f32x4 h1 = *(const f32x4*)(src + col0 + 4) + acc[ai][bj][m][1];
;                         *(f32x4*)(dst + col0) = h0; *(f32x4*)(dst + col0 + 4) = h1;
;                         if (P) { u32x4 w; w.x = cvtpk(h0[0], h0[1]); w.y = cvtpk(h0[2], h0[3]); w.z = cvtpk(h1[0], h1[1]); w.w = cvtpk(h1[2], h1[3]);
;                             *(u32x4*)(P + (size_t)grow * DM + col0) = w; }
;                         ss += (h0[0] * h0[0] + h0[1] * h0[1]) + (h0[2] * h0[2] + h0[3] * h0[3]) + (h1[0] * h1[0] + h1[1] * h1[1]) + (h1[2] * h1[2] + h1[3] * h1[3]);
;                     }
	v_pk_add_f32 v[78:79], v[78:79], v[142:143]
	v_pk_add_f32 v[80:81], v[80:81], v[144:145]
	v_pk_add_f32 v[74:75], v[74:75], v[146:147]
	v_pk_add_f32 v[76:77], v[76:77], v[148:149]
	v_pk_add_f32 v[70:71], v[70:71], v[158:159]
	v_pk_add_f32 v[72:73], v[72:73], v[160:161]
	v_pk_add_f32 v[66:67], v[66:67], v[204:205]
	v_pk_add_f32 v[68:69], v[68:69], v[206:207]
	v_cvt_pk_bf16_f32 v142, v78, v79
	v_cvt_pk_bf16_f32 v143, v80, v81
	v_cvt_pk_bf16_f32 v144, v74, v75
	v_cvt_pk_bf16_f32 v145, v76, v77
	v_cvt_pk_bf16_f32 v146, v70, v71
	v_cvt_pk_bf16_f32 v147, v72, v73
	v_cvt_pk_bf16_f32 v148, v66, v67
	v_cvt_pk_bf16_f32 v149, v68, v69
	v_mul_f32_e32 v163, v78, v78
	v_mul_f32_e32 v200, v79, v79
	v_fmac_f32_e32 v163, v80, v80
	v_fmac_f32_e32 v200, v81, v81
	v_fmac_f32_e32 v163, v74, v74
	v_fmac_f32_e32 v200, v75, v75
	v_fmac_f32_e32 v163, v76, v76
	v_fmac_f32_e32 v200, v77, v77
	v_fmac_f32_e32 v163, v70, v70
	v_fmac_f32_e32 v200, v71, v71
	v_fmac_f32_e32 v163, v72, v72
	v_fmac_f32_e32 v200, v73, v73
	v_fmac_f32_e32 v163, v66, v66
	v_fmac_f32_e32 v200, v67, v67
	v_fmac_f32_e32 v163, v68, v68
	v_fmac_f32_e32 v200, v69, v69
	ds_bpermute_b32 v78, v232, v78
	ds_bpermute_b32 v79, v232, v79
	ds_bpermute_b32 v80, v232, v80
	ds_bpermute_b32 v81, v232, v81
	ds_bpermute_b32 v74, v232, v74
	ds_bpermute_b32 v75, v232, v75
	ds_bpermute_b32 v76, v232, v76
	ds_bpermute_b32 v77, v232, v77
	ds_bpermute_b32 v70, v232, v70
	ds_bpermute_b32 v71, v232, v71
	ds_bpermute_b32 v72, v232, v72
	ds_bpermute_b32 v73, v232, v73
	ds_bpermute_b32 v66, v232, v66
	ds_bpermute_b32 v67, v232, v67
	ds_bpermute_b32 v68, v232, v68
	ds_bpermute_b32 v69, v232, v69
	ds_bpermute_b32 v142, v232, v142
	ds_bpermute_b32 v143, v232, v143
	ds_bpermute_b32 v144, v232, v144
	ds_bpermute_b32 v145, v232, v145
	ds_bpermute_b32 v146, v232, v146
	ds_bpermute_b32 v147, v232, v147
	ds_bpermute_b32 v148, v232, v148
	ds_bpermute_b32 v149, v232, v149
	s_waitcnt lgkmcnt(0)
	global_store_dwordx4 v233, v[78:81], s[50:51]
	global_store_dwordx4 v233, v[74:77], s[50:51] offset:16
	global_store_dwordx4 v233, v[70:73], s[50:51] offset:512
	global_store_dwordx4 v233, v[66:69], s[50:51] offset:528
	global_store_dwordx4 v234, v[142:145], s[6:7]
	global_store_dwordx4 v234, v[146:149], s[6:7] offset:256
	v_add_f32_e32 v66, v163, v200
	s_add_u32 s50, s50, 0x50000
	s_addc_u32 s51, s51, 0
	s_add_u32 s6, s6, 0x28000
	s_addc_u32 s7, s7, 0
	global_load_dwordx4 v[142:145], v150, s[48:49]
	global_load_dwordx4 v[146:149], v150, s[48:49] offset:16
	global_load_dwordx4 v[158:161], v150, s[48:49] offset:512
	global_load_dwordx4 v[204:207], v150, s[48:49] offset:528
	s_waitcnt vmcnt(30)
	v_pk_add_f32 v[62:63], v[62:63], v[168:169]
	v_pk_add_f32 v[64:65], v[64:65], v[170:171]
	v_pk_add_f32 v[58:59], v[58:59], v[172:173]
	v_pk_add_f32 v[60:61], v[60:61], v[174:175]
	v_pk_add_f32 v[54:55], v[54:55], v[176:177]
	v_pk_add_f32 v[56:57], v[56:57], v[178:179]
	v_pk_add_f32 v[50:51], v[50:51], v[180:181]
	v_pk_add_f32 v[52:53], v[52:53], v[182:183]
	v_cvt_pk_bf16_f32 v168, v62, v63
	v_cvt_pk_bf16_f32 v169, v64, v65
	v_cvt_pk_bf16_f32 v170, v58, v59
	v_cvt_pk_bf16_f32 v171, v60, v61
	v_cvt_pk_bf16_f32 v172, v54, v55
	v_cvt_pk_bf16_f32 v173, v56, v57
	v_cvt_pk_bf16_f32 v174, v50, v51
	v_cvt_pk_bf16_f32 v175, v52, v53
	v_mul_f32_e32 v163, v62, v62
	v_mul_f32_e32 v200, v63, v63
	v_fmac_f32_e32 v163, v64, v64
	v_fmac_f32_e32 v200, v65, v65
	v_fmac_f32_e32 v163, v58, v58
	v_fmac_f32_e32 v200, v59, v59
	v_fmac_f32_e32 v163, v60, v60
	v_fmac_f32_e32 v200, v61, v61
	v_fmac_f32_e32 v163, v54, v54
	v_fmac_f32_e32 v200, v55, v55
	v_fmac_f32_e32 v163, v56, v56
	v_fmac_f32_e32 v200, v57, v57
	v_fmac_f32_e32 v163, v50, v50
	v_fmac_f32_e32 v200, v51, v51
	v_fmac_f32_e32 v163, v52, v52
	v_fmac_f32_e32 v200, v53, v53
	ds_bpermute_b32 v62, v232, v62
	ds_bpermute_b32 v63, v232, v63
	ds_bpermute_b32 v64, v232, v64
	ds_bpermute_b32 v65, v232, v65
	ds_bpermute_b32 v58, v232, v58
	ds_bpermute_b32 v59, v232, v59
	ds_bpermute_b32 v60, v232, v60
	ds_bpermute_b32 v61, v232, v61
	ds_bpermute_b32 v54, v232, v54
	ds_bpermute_b32 v55, v232, v55
	ds_bpermute_b32 v56, v232, v56
	ds_bpermute_b32 v57, v232, v57
	ds_bpermute_b32 v50, v232, v50
	ds_bpermute_b32 v51, v232, v51
	ds_bpermute_b32 v52, v232, v52
	ds_bpermute_b32 v53, v232, v53
	ds_bpermute_b32 v168, v232, v168
	ds_bpermute_b32 v169, v232, v169
	ds_bpermute_b32 v170, v232, v170
	ds_bpermute_b32 v171, v232, v171
	ds_bpermute_b32 v172, v232, v172
	ds_bpermute_b32 v173, v232, v173
	ds_bpermute_b32 v174, v232, v174
	ds_bpermute_b32 v175, v232, v175
	s_waitcnt lgkmcnt(0)
	global_store_dwordx4 v233, v[62:65], s[50:51]
	global_store_dwordx4 v233, v[58:61], s[50:51] offset:16
	global_store_dwordx4 v233, v[54:57], s[50:51] offset:512
	global_store_dwordx4 v233, v[50:53], s[50:51] offset:528
	global_store_dwordx4 v234, v[168:171], s[6:7]
	global_store_dwordx4 v234, v[172:175], s[6:7] offset:256
	v_add_f32_e32 v50, v163, v200
	s_add_u32 s50, s50, 0x10000
	s_addc_u32 s51, s51, 0
	s_add_u32 s6, s6, 0x8000
	s_addc_u32 s7, s7, 0
	s_waitcnt vmcnt(26)
; __device__ __forceinline__ unsigned cvtpk(float lo, float hi) { f32x2 v = {lo, hi}; bf16x2_t b = __builtin_convertvector(v, bf16x2_t); return __builtin_bit_cast(unsigned, b); }
;     __device__ __forceinline__ void operator()(const f32x4 (&acc)[2][2][4][2], const pg8::Unit& u, int wr, int wc, int fr, int fq) const {
;     ...
;                     for (int bj = 0; bj < 2; ++bj) {
;                         const int col0 = u.pn * 256 + bj * 128 + wc * 32 + 8 * fq;
;                         const f32x4 h0 = *(const f32x4*)(src + col0) + acc[ai][bj][m][0];
;                         const f32x4 h1 = *(const f32x4*)(src + col0 + 4) + acc[ai][bj][m][1];
;                         *(f32x4*)(dst + col0) = h0; *(f32x4*)(dst + col0 + 4) = h1;
;                         if (P) { u32x4 w; w.x = cvtpk(h0[0], h0[1]); w.y = cvtpk(h0[2], h0[3]); w.z = cvtpk(h1[0], h1[1]); w.w = cvtpk(h1[2], h1[3]);
;                             *(u32x4*)(P + (size_t)grow * DM + col0) = w; }
;                         ss += (h0[0] * h0[0] + h0[1] * h0[1]) + (h0[2] * h0[2] + h0[3] * h0[3]) + (h1[0] * h1[0] + h1[1] * h1[1]) + (h1[2] * h1[2] + h1[3] * h1[3]);
;                     }
	v_pk_add_f32 v[46:47], v[46:47], v[184:185]
	v_pk_add_f32 v[48:49], v[48:49], v[186:187]
	v_pk_add_f32 v[42:43], v[42:43], v[188:189]
	v_pk_add_f32 v[44:45], v[44:45], v[190:191]
	v_pk_add_f32 v[38:39], v[38:39], v[192:193]
	v_pk_add_f32 v[40:41], v[40:41], v[194:195]
	v_pk_add_f32 v[34:35], v[34:35], v[196:197]
	v_pk_add_f32 v[36:37], v[36:37], v[198:199]
	v_cvt_pk_bf16_f32 v184, v46, v47
	v_cvt_pk_bf16_f32 v185, v48, v49
	v_cvt_pk_bf16_f32 v186, v42, v43
	v_cvt_pk_bf16_f32 v187, v44, v45
	v_cvt_pk_bf16_f32 v188, v38, v39
	v_cvt_pk_bf16_f32 v189, v40, v41
	v_cvt_pk_bf16_f32 v190, v34, v35
	v_cvt_pk_bf16_f32 v191, v36, v37
	v_mul_f32_e32 v163, v46, v46
	v_mul_f32_e32 v200, v47, v47
	v_fmac_f32_e32 v163, v48, v48
	v_fmac_f32_e32 v200, v49, v49
	v_fmac_f32_e32 v163, v42, v42
	v_fmac_f32_e32 v200, v43, v43
	v_fmac_f32_e32 v163, v44, v44
	v_fmac_f32_e32 v200, v45, v45
	v_fmac_f32_e32 v163, v38, v38
	v_fmac_f32_e32 v200, v39, v39
	v_fmac_f32_e32 v163, v40, v40
	v_fmac_f32_e32 v200, v41, v41
	v_fmac_f32_e32 v163, v34, v34
	v_fmac_f32_e32 v200, v35, v35
	v_fmac_f32_e32 v163, v36, v36
	v_fmac_f32_e32 v200, v37, v37
	ds_bpermute_b32 v46, v232, v46
	ds_bpermute_b32 v47, v232, v47
	ds_bpermute_b32 v48, v232, v48
	ds_bpermute_b32 v49, v232, v49
	ds_bpermute_b32 v42, v232, v42
	ds_bpermute_b32 v43, v232, v43
	ds_bpermute_b32 v44, v232, v44
	ds_bpermute_b32 v45, v232, v45
	ds_bpermute_b32 v38, v232, v38
	ds_bpermute_b32 v39, v232, v39
	ds_bpermute_b32 v40, v232, v40
	ds_bpermute_b32 v41, v232, v41
	ds_bpermute_b32 v34, v232, v34
	ds_bpermute_b32 v35, v232, v35
	ds_bpermute_b32 v36, v232, v36
	ds_bpermute_b32 v37, v232, v37
	ds_bpermute_b32 v184, v232, v184
	ds_bpermute_b32 v185, v232, v185
	ds_bpermute_b32 v186, v232, v186
	ds_bpermute_b32 v187, v232, v187
	ds_bpermute_b32 v188, v232, v188
	ds_bpermute_b32 v189, v232, v189
	ds_bpermute_b32 v190, v232, v190
	ds_bpermute_b32 v191, v232, v191
	s_waitcnt lgkmcnt(0)
	global_store_dwordx4 v233, v[46:49], s[50:51]
	global_store_dwordx4 v233, v[42:45], s[50:51] offset:16
	global_store_dwordx4 v233, v[38:41], s[50:51] offset:512
	global_store_dwordx4 v233, v[34:37], s[50:51] offset:528
	global_store_dwordx4 v234, v[184:187], s[6:7]
	global_store_dwordx4 v234, v[188:191], s[6:7] offset:256
	v_add_f32_e32 v34, v163, v200
	s_add_u32 s50, s50, 0x10000
	s_addc_u32 s51, s51, 0
	s_add_u32 s6, s6, 0x8000
	s_addc_u32 s7, s7, 0
	s_waitcnt vmcnt(22)
	v_pk_add_f32 v[28:29], v[28:29], v[216:217]
	v_pk_add_f32 v[30:31], v[30:31], v[218:219]
	v_pk_add_f32 v[24:25], v[24:25], v[220:221]
	v_pk_add_f32 v[26:27], v[26:27], v[222:223]
	v_pk_add_f32 v[20:21], v[20:21], v[224:225]
	v_pk_add_f32 v[22:23], v[22:23], v[226:227]
	v_pk_add_f32 v[16:17], v[16:17], v[228:229]
	v_pk_add_f32 v[18:19], v[18:19], v[230:231]
	v_cvt_pk_bf16_f32 v216, v28, v29
	v_cvt_pk_bf16_f32 v217, v30, v31
	v_cvt_pk_bf16_f32 v218, v24, v25
	v_cvt_pk_bf16_f32 v219, v26, v27
	v_cvt_pk_bf16_f32 v220, v20, v21
	v_cvt_pk_bf16_f32 v221, v22, v23
	v_cvt_pk_bf16_f32 v222, v16, v17
	v_cvt_pk_bf16_f32 v223, v18, v19
	v_mul_f32_e32 v163, v28, v28
	v_mul_f32_e32 v200, v29, v29
	v_fmac_f32_e32 v163, v30, v30
	v_fmac_f32_e32 v200, v31, v31
	v_fmac_f32_e32 v163, v24, v24
	v_fmac_f32_e32 v200, v25, v25
	v_fmac_f32_e32 v163, v26, v26
	v_fmac_f32_e32 v200, v27, v27
	v_fmac_f32_e32 v163, v20, v20
	v_fmac_f32_e32 v200, v21, v21
	v_fmac_f32_e32 v163, v22, v22
	v_fmac_f32_e32 v200, v23, v23
	v_fmac_f32_e32 v163, v16, v16
	v_fmac_f32_e32 v200, v17, v17
	v_fmac_f32_e32 v163, v18, v18
	v_fmac_f32_e32 v200, v19, v19
	ds_bpermute_b32 v28, v232, v28
	ds_bpermute_b32 v29, v232, v29
	ds_bpermute_b32 v30, v232, v30
	ds_bpermute_b32 v31, v232, v31
	ds_bpermute_b32 v24, v232, v24
	ds_bpermute_b32 v25, v232, v25
	ds_bpermute_b32 v26, v232, v26
	ds_bpermute_b32 v27, v232, v27
	ds_bpermute_b32 v20, v232, v20
	ds_bpermute_b32 v21, v232, v21
	ds_bpermute_b32 v22, v232, v22
	ds_bpermute_b32 v23, v232, v23
	ds_bpermute_b32 v16, v232, v16
	ds_bpermute_b32 v17, v232, v17
	ds_bpermute_b32 v18, v232, v18
	ds_bpermute_b32 v19, v232, v19
	ds_bpermute_b32 v216, v232, v216
	ds_bpermute_b32 v217, v232, v217
	ds_bpermute_b32 v218, v232, v218
	ds_bpermute_b32 v219, v232, v219
	ds_bpermute_b32 v220, v232, v220
	ds_bpermute_b32 v221, v232, v221
	ds_bpermute_b32 v222, v232, v222
	ds_bpermute_b32 v223, v232, v223
	s_waitcnt lgkmcnt(0)
	global_store_dwordx4 v233, v[28:31], s[50:51]
	global_store_dwordx4 v233, v[24:27], s[50:51] offset:16
	global_store_dwordx4 v233, v[20:23], s[50:51] offset:512
	global_store_dwordx4 v233, v[16:19], s[50:51] offset:528
	global_store_dwordx4 v234, v[216:219], s[6:7]
	global_store_dwordx4 v234, v[220:223], s[6:7] offset:256
	v_add_f32_e32 v16, v163, v200
	s_add_u32 s50, s50, 0x10000
	s_addc_u32 s51, s51, 0
	s_add_u32 s6, s6, 0x8000
	s_addc_u32 s7, s7, 0
	s_waitcnt vmcnt(18)
; __device__ __forceinline__ unsigned cvtpk(float lo, float hi) { f32x2 v = {lo, hi}; bf16x2_t b = __builtin_convertvector(v, bf16x2_t); return __builtin_bit_cast(unsigned, b); }
;     __device__ __forceinline__ void operator()(const f32x4 (&acc)[2][2][4][2], const pg8::Unit& u, int wr, int wc, int fr, int fq) const {
;     ...
;                     for (int bj = 0; bj < 2; ++bj) {
;                         const int col0 = u.pn * 256 + bj * 128 + wc * 32 + 8 * fq;
;                         const f32x4 h0 = *(const f32x4*)(src + col0) + acc[ai][bj][m][0];
;                         const f32x4 h1 = *(const f32x4*)(src + col0 + 4) + acc[ai][bj][m][1];
;                         *(f32x4*)(dst + col0) = h0; *(f32x4*)(dst + col0 + 4) = h1;
;                         if (P) { u32x4 w; w.x = cvtpk(h0[0], h0[1]); w.y = cvtpk(h0[2], h0[3]); w.z = cvtpk(h1[0], h1[1]); w.w = cvtpk(h1[2], h1[3]);
;                             *(u32x4*)(P + (size_t)grow * DM + col0) = w; }
;                         ss += (h0[0] * h0[0] + h0[1] * h0[1]) + (h0[2] * h0[2] + h0[3] * h0[3]) + (h1[0] * h1[0] + h1[1] * h1[1]) + (h1[2] * h1[2] + h1[3] * h1[3]);
;                     }
;                 }
;                 ss += __shfl_xor(ss, 16); ss += __shfl_xor(ss, 32);
;                 if (ok && fq == 0 && rowss_next) atomicAdd(rowss_next + grow, (u64)(ss * SS_SCALE));
	v_pk_add_f32 v[12:13], v[12:13], v[142:143]
	v_pk_add_f32 v[14:15], v[14:15], v[144:145]
	v_pk_add_f32 v[8:9], v[8:9], v[146:147]
	v_pk_add_f32 v[10:11], v[10:11], v[148:149]
	v_pk_add_f32 v[4:5], v[4:5], v[158:159]
	v_pk_add_f32 v[6:7], v[6:7], v[160:161]
	v_pk_add_f32 v[0:1], v[0:1], v[204:205]
	v_pk_add_f32 v[2:3], v[2:3], v[206:207]
	v_cvt_pk_bf16_f32 v142, v12, v13
	v_cvt_pk_bf16_f32 v143, v14, v15
	v_cvt_pk_bf16_f32 v144, v8, v9
	v_cvt_pk_bf16_f32 v145, v10, v11
	v_cvt_pk_bf16_f32 v146, v4, v5
	v_cvt_pk_bf16_f32 v147, v6, v7
	v_cvt_pk_bf16_f32 v148, v0, v1
	v_cvt_pk_bf16_f32 v149, v2, v3
	v_mul_f32_e32 v163, v12, v12
	v_mul_f32_e32 v200, v13, v13
	v_fmac_f32_e32 v163, v14, v14
	v_fmac_f32_e32 v200, v15, v15
	v_fmac_f32_e32 v163, v8, v8
	v_fmac_f32_e32 v200, v9, v9
	v_fmac_f32_e32 v163, v10, v10
	v_fmac_f32_e32 v200, v11, v11
	v_fmac_f32_e32 v163, v4, v4
	v_fmac_f32_e32 v200, v5, v5
	v_fmac_f32_e32 v163, v6, v6
	v_fmac_f32_e32 v200, v7, v7
	v_fmac_f32_e32 v163, v0, v0
	v_fmac_f32_e32 v200, v1, v1
	v_fmac_f32_e32 v163, v2, v2
	v_fmac_f32_e32 v200, v3, v3
	ds_bpermute_b32 v12, v232, v12
	ds_bpermute_b32 v13, v232, v13
	ds_bpermute_b32 v14, v232, v14
	ds_bpermute_b32 v15, v232, v15
	ds_bpermute_b32 v8, v232, v8
	ds_bpermute_b32 v9, v232, v9
	ds_bpermute_b32 v10, v232, v10
	ds_bpermute_b32 v11, v232, v11
	ds_bpermute_b32 v4, v232, v4
	ds_bpermute_b32 v5, v232, v5
	ds_bpermute_b32 v6, v232, v6
	ds_bpermute_b32 v7, v232, v7
	ds_bpermute_b32 v0, v232, v0
	ds_bpermute_b32 v1, v232, v1
	ds_bpermute_b32 v2, v232, v2
	ds_bpermute_b32 v3, v232, v3
	ds_bpermute_b32 v142, v232, v142
	ds_bpermute_b32 v143, v232, v143
	ds_bpermute_b32 v144, v232, v144
	ds_bpermute_b32 v145, v232, v145
	ds_bpermute_b32 v146, v232, v146
	ds_bpermute_b32 v147, v232, v147
	ds_bpermute_b32 v148, v232, v148
	ds_bpermute_b32 v149, v232, v149
	s_waitcnt lgkmcnt(0)
	global_store_dwordx4 v233, v[12:15], s[50:51]
	global_store_dwordx4 v233, v[8:11], s[50:51] offset:16
	global_store_dwordx4 v233, v[4:7], s[50:51] offset:512
	global_store_dwordx4 v233, v[0:3], s[50:51] offset:528
	global_store_dwordx4 v234, v[142:145], s[6:7]
	global_store_dwordx4 v234, v[146:149], s[6:7] offset:256
	v_add_f32_e32 v0, v163, v200
	v_mbcnt_lo_u32_b32 v201, -1, 0
	v_mbcnt_hi_u32_b32 v201, -1, v201
	v_xor_b32_e32 v208, 16, v201
	v_xor_b32_e32 v209, 32, v201
	v_lshlrev_b32_e32 v208, 2, v208
	v_lshlrev_b32_e32 v209, 2, v209
	ds_bpermute_b32 v115, v208, v114
	ds_bpermute_b32 v99, v208, v98
	ds_bpermute_b32 v83, v208, v82
	ds_bpermute_b32 v67, v208, v66
	ds_bpermute_b32 v51, v208, v50
	ds_bpermute_b32 v35, v208, v34
	ds_bpermute_b32 v17, v208, v16
	ds_bpermute_b32 v1, v208, v0
	s_waitcnt lgkmcnt(0)
	v_add_f32_e32 v114, v114, v115
	v_add_f32_e32 v98, v98, v99
	v_add_f32_e32 v82, v82, v83
	v_add_f32_e32 v66, v66, v67
	v_add_f32_e32 v50, v50, v51
	v_add_f32_e32 v34, v34, v35
	v_add_f32_e32 v16, v16, v17
	v_add_f32_e32 v0, v0, v1
	ds_bpermute_b32 v115, v209, v114
	ds_bpermute_b32 v99, v209, v98
	ds_bpermute_b32 v83, v209, v82
	ds_bpermute_b32 v67, v209, v66
	ds_bpermute_b32 v51, v209, v50
	ds_bpermute_b32 v35, v209, v34
	ds_bpermute_b32 v17, v209, v16
	ds_bpermute_b32 v1, v209, v0
	s_waitcnt lgkmcnt(0)
	v_add_f32_e32 v114, v114, v115
	v_add_f32_e32 v98, v98, v99
	v_add_f32_e32 v82, v82, v83
	v_add_f32_e32 v66, v66, v67
	v_add_f32_e32 v50, v50, v51
	v_add_f32_e32 v34, v34, v35
	v_add_f32_e32 v16, v16, v17
	v_add_f32_e32 v0, v0, v1
	s_and_saveexec_b64 s[48:49], s[2:3]
	v_mul_f32_e32 v114, 0x49800000, v114
	v_trunc_f32_e32 v114, v114
	v_mul_f32_e32 v115, 0x2f800000, v114
	v_floor_f32_e32 v115, v115
	v_fmac_f32_e32 v114, 0xcf800000, v115
	v_cvt_u32_f32_e32 v116, v114
	v_cvt_u32_f32_e32 v117, v115
	global_atomic_add_x2 v162, v[116:117], s[8:9]
	v_mul_f32_e32 v98, 0x49800000, v98
	v_trunc_f32_e32 v98, v98
	v_mul_f32_e32 v99, 0x2f800000, v98
	v_floor_f32_e32 v99, v99
	v_fmac_f32_e32 v98, 0xcf800000, v99
	v_cvt_u32_f32_e32 v100, v98
	v_cvt_u32_f32_e32 v101, v99
	global_atomic_add_x2 v162, v[100:101], s[8:9] offset:128
	v_mul_f32_e32 v82, 0x49800000, v82
	v_trunc_f32_e32 v82, v82
	v_mul_f32_e32 v83, 0x2f800000, v82
	v_floor_f32_e32 v83, v83
	v_fmac_f32_e32 v82, 0xcf800000, v83
	v_cvt_u32_f32_e32 v84, v82
	v_cvt_u32_f32_e32 v85, v83
	global_atomic_add_x2 v162, v[84:85], s[8:9] offset:256
	v_mul_f32_e32 v66, 0x49800000, v66
	v_trunc_f32_e32 v66, v66
	v_mul_f32_e32 v67, 0x2f800000, v66
	v_floor_f32_e32 v67, v67
	v_fmac_f32_e32 v66, 0xcf800000, v67
	v_cvt_u32_f32_e32 v68, v66
	v_cvt_u32_f32_e32 v69, v67
	global_atomic_add_x2 v162, v[68:69], s[8:9] offset:384
	v_mul_f32_e32 v50, 0x49800000, v50
	v_trunc_f32_e32 v50, v50
	v_mul_f32_e32 v51, 0x2f800000, v50
	v_floor_f32_e32 v51, v51
	v_fmac_f32_e32 v50, 0xcf800000, v51
	v_cvt_u32_f32_e32 v52, v50
	v_cvt_u32_f32_e32 v53, v51
	global_atomic_add_x2 v162, v[52:53], s[8:9] offset:1024
	v_mul_f32_e32 v34, 0x49800000, v34
	v_trunc_f32_e32 v34, v34
	v_mul_f32_e32 v35, 0x2f800000, v34
	v_floor_f32_e32 v35, v35
	v_fmac_f32_e32 v34, 0xcf800000, v35
	v_cvt_u32_f32_e32 v36, v34
	v_cvt_u32_f32_e32 v37, v35
	global_atomic_add_x2 v162, v[36:37], s[8:9] offset:1152
	v_mul_f32_e32 v16, 0x49800000, v16
	v_trunc_f32_e32 v16, v16
	v_mul_f32_e32 v17, 0x2f800000, v16
	v_floor_f32_e32 v17, v17
	v_fmac_f32_e32 v16, 0xcf800000, v17
	v_cvt_u32_f32_e32 v18, v16
	v_cvt_u32_f32_e32 v19, v17
	global_atomic_add_x2 v162, v[18:19], s[8:9] offset:1280
	v_mul_f32_e32 v0, 0x49800000, v0
	v_trunc_f32_e32 v0, v0
	v_mul_f32_e32 v1, 0x2f800000, v0
	v_floor_f32_e32 v1, v1
	v_fmac_f32_e32 v0, 0xcf800000, v1
	v_cvt_u32_f32_e32 v2, v0
	v_cvt_u32_f32_e32 v3, v1
	global_atomic_add_x2 v162, v[2:3], s[8:9] offset:1408
	s_mov_b64 exec, s[48:49]
	s_branch .Lepi_done_dn
